# P11 conv-silu epilogue: IEEE div expansion -> v_rcp_f32+v_mul (f32), removed dead zero-inits before full-row DPP rotates
# speedup vs baseline: 1.0213x; 1.0213x over previous
; __device__ __forceinline__ float dpp_ror1(float x) { return __int_as_float(__builtin_amdgcn_update_dpp(0, __float_as_int(x), 0x121, 0xf, 0xf, false)); }
; __device__ __forceinline__ float dpp_ror2(float x) { return __int_as_float(__builtin_amdgcn_update_dpp(0, __float_as_int(x), 0x122, 0xf, 0xf, false)); }
;     __device__ __forceinline__ float rsq(int row) const { const f32x4 q0 = *(const f32x4*)(pssq + (size_t)row * 8), q1 = *(const f32x4*)(pssq + (size_t)row * 8 + 4);
;         return rsqrtf(((q0.x + q0.y) + (q0.z + q0.w) + (q1.x + q1.y) + (q1.z + q1.w)) * (1.f / D) + EPS); }
;     __device__ __forceinline__ void operator()(const f32x4 (&acc)[2][2][4][2], const Unit& u, int wr, int wc, int fr, int fq) const {
;     ...
;             for (int m = 0; m < 4; ++m) { const int row = rowb + ai * HALF + m * 16; const float rs = rsq(row);
;                 f32x4 g[2], a[2];
; #pragma unroll
;                 for (int n = 0; n < 2; ++n) { g[n] = acc[ai][0][m][n] * rs; const f32x4 up = acc[ai][1][m][n] * rs;
; #pragma unroll
;                     for (int e = 0; e < 4; ++e) { const float r1c = dpp_ror1(g[n][e]), r1p = dpp_ror1(gprev[n][e]), r2c = dpp_ror2(g[n][e]), r2p = dpp_ror2(gprev[n][e]);
;                         const float p1 = fr >= 1 ? r1c : r1p, p2 = fr >= 2 ? r2c : r2p;
;                         const float c = bb[n][e] + w0[n][e] * p2 + w1[n][e] * p1 + w2[n][e] * g[n][e]; a[n][e] = c / (1.f + __expf(-c)) * up[e]; }
;                     if (ai == 0 && m == 0 && wr == 0 && fr < 2) { *(f32x4*)(firstg + ((size_t)u.pm * 2 + fr) * FF + ch0 + 4 * n) = g[n]; *(f32x4*)(firstup + ((size_t)u.pm * 2 + fr) * FF + ch0 + 4 * n) = up; }
.LBB0_793:
	v_ashrrev_i32_e32 v185, 31, v184
	v_lshlrev_b64 v[214:215], 5, v[184:185]
	v_lshl_add_u64 v[214:215], s[46:47], 0, v[214:215]
	global_load_dwordx4 v[236:239], v[214:215], off
	global_load_dwordx4 v[240:243], v[214:215], off offset:16
	s_ashr_i32 s19, s18, 31
	s_lshl_b64 s[76:77], s[18:19], 1
	v_mov_b32_dpp v230, v190 row_ror:1 row_mask:0xf bank_mask:0xf
	v_mov_b32_dpp v231, v190 row_ror:2 row_mask:0xf bank_mask:0xf
	v_mov_b32_dpp v234, v191 row_ror:1 row_mask:0xf bank_mask:0xf
	v_mov_b32_dpp v235, v191 row_ror:2 row_mask:0xf bank_mask:0xf
	v_lshl_add_u64 v[190:191], s[76:77], 0, v[196:197]
	v_mov_b32_dpp v222, v198 row_ror:1 row_mask:0xf bank_mask:0xf
	v_mov_b32_dpp v223, v198 row_ror:2 row_mask:0xf bank_mask:0xf
	v_mov_b32_dpp v226, v199 row_ror:1 row_mask:0xf bank_mask:0xf
	v_mov_b32_dpp v227, v199 row_ror:2 row_mask:0xf bank_mask:0xf
	v_mad_u64_u32 v[198:199], s[16:17], v190, s97, 0
	v_mad_i32_i24 v199, v191, s97, v199
	s_waitcnt vmcnt(0)
	v_mov_b32_e32 v190, v237
	v_mov_b32_e32 v191, v238
	v_mov_b32_e32 v237, v239
	v_mov_b32_e32 v214, v242
	v_mov_b32_e32 v215, v240
	v_mov_b32_e32 v240, v243
	v_pk_add_f32 v[190:191], v[190:191], v[236:237]
	v_pk_add_f32 v[214:215], v[214:215], v[240:241]
	v_add_f32_e32 v185, v190, v191
	v_add_f32_e32 v185, v185, v215
	v_add_f32_e32 v185, v214, v185
	v_fmamk_f32 v185, v185, 0x3a000000, v178
	v_mul_f32_e32 v190, 0x4b800000, v185
	v_cmp_gt_f32_e32 vcc, s96, v185
	v_lshl_add_u64 v[214:215], s[48:49], 0, v[198:199]
	s_nop 0
	v_cndmask_b32_e32 v185, v185, v190, vcc
	v_rsq_f32_e32 v185, v185
	v_lshl_add_u64 v[190:191], s[50:51], 0, v[198:199]
	v_lshl_add_u64 v[190:191], v[190:191], 0, v[188:189]
	v_lshl_add_u64 v[188:189], v[214:215], 0, v[188:189]
	v_mul_f32_e32 v198, 0x45800000, v185
	v_cndmask_b32_e32 v198, v185, v198, vcc
	v_pk_mul_f32 v[158:159], v[158:159], v[198:199] op_sel_hi:[1,0]
	v_pk_mul_f32 v[156:157], v[156:157], v[198:199] op_sel_hi:[1,0]
	v_pk_mul_f32 v[154:155], v[154:155], v[198:199] op_sel_hi:[1,0]
	v_pk_mul_f32 v[152:153], v[152:153], v[198:199] op_sel_hi:[1,0]
	v_mov_b32_dpp v228, v156 row_ror:1 row_mask:0xf bank_mask:0xf
	v_mov_b32_dpp v229, v156 row_ror:2 row_mask:0xf bank_mask:0xf
	v_mov_b32_dpp v232, v157 row_ror:1 row_mask:0xf bank_mask:0xf
	v_mov_b32_dpp v233, v157 row_ror:2 row_mask:0xf bank_mask:0xf
	v_mov_b32_dpp v220, v158 row_ror:1 row_mask:0xf bank_mask:0xf
	v_mov_b32_dpp v221, v158 row_ror:2 row_mask:0xf bank_mask:0xf
	v_mov_b32_dpp v224, v159 row_ror:1 row_mask:0xf bank_mask:0xf
	v_mov_b32_dpp v225, v159 row_ror:2 row_mask:0xf bank_mask:0xf
	s_and_saveexec_b64 s[18:19], s[58:59]
	s_cbranch_execz .LBB0_795
	global_store_dwordx4 v[188:189], v[156:159], off
	global_store_dwordx4 v[190:191], v[152:155], off
; __device__ __forceinline__ unsigned pk2(float lo, float hi) { f32x2_t v = {lo, hi}; bf16x2_t b = __builtin_convertvector(v, bf16x2_t); return __builtin_bit_cast(unsigned, b); }
; __device__ __forceinline__ float dpp_ror1(float x) { return __int_as_float(__builtin_amdgcn_update_dpp(0, __float_as_int(x), 0x121, 0xf, 0xf, false)); }
; __device__ __forceinline__ float dpp_ror2(float x) { return __int_as_float(__builtin_amdgcn_update_dpp(0, __float_as_int(x), 0x122, 0xf, 0xf, false)); }
;     __device__ __forceinline__ void operator()(const f32x4 (&acc)[2][2][4][2], const Unit& u, int wr, int wc, int fr, int fq) const {
;     ...
;                 for (int n = 0; n < 2; ++n) { g[n] = acc[ai][0][m][n] * rs; const f32x4 up = acc[ai][1][m][n] * rs;
; #pragma unroll
;                     for (int e = 0; e < 4; ++e) { const float r1c = dpp_ror1(g[n][e]), r1p = dpp_ror1(gprev[n][e]), r2c = dpp_ror2(g[n][e]), r2p = dpp_ror2(gprev[n][e]);
;                         const float p1 = fr >= 1 ? r1c : r1p, p2 = fr >= 2 ? r2c : r2p;
;                         const float c = bb[n][e] + w0[n][e] * p2 + w1[n][e] * p1 + w2[n][e] * g[n][e]; a[n][e] = c / (1.f + __expf(-c)) * up[e]; }
;                     if (ai == 0 && m == 0 && wr == 0 && fr < 2) { *(f32x4*)(firstg + ((size_t)u.pm * 2 + fr) * FF + ch0 + 4 * n) = g[n]; *(f32x4*)(firstup + ((size_t)u.pm * 2 + fr) * FF + ch0 + 4 * n) = up; }
;                     if (ai == 1 && m == 3 && wr == 1 && fr >= 14) *(f32x4*)(lastg + ((size_t)u.pm * 2 + (fr - 14)) * FF + ch0 + 4 * n) = g[n]; }
;                 if (!(ai == 0 && m == 0 && wr == 0 && fr < 2)) { u32x4 w; w.x = pk2(a[0][0], a[0][1]); w.y = pk2(a[0][2], a[0][3]); w.z = pk2(a[1][0], a[1][1]); w.w = pk2(a[1][2], a[1][3]);
;                     *(u32x4*)(ACT + (size_t)row * FF + ch0) = w; }
.LBB0_795:
	s_or_b64 exec, exec, s[18:19]
	v_mov_b32_e32 v199, v198
	v_mov_b32_e32 v214, v198
	v_mov_b32_e32 v215, v198
	v_pk_mul_f32 v[150:151], v[150:151], v[214:215]
	v_pk_mul_f32 v[148:149], v[148:149], v[198:199]
	v_pk_mul_f32 v[146:147], v[146:147], v[214:215]
	v_pk_mul_f32 v[144:145], v[144:145], v[198:199]
	v_mov_b32_dpp v198, v212 row_ror:1 row_mask:0xf bank_mask:0xf
	v_mov_b32_dpp v213, v212 row_ror:2 row_mask:0xf bank_mask:0xf
	v_mov_b32_dpp v214, v219 row_ror:1 row_mask:0xf bank_mask:0xf
	v_mov_b32_dpp v216, v219 row_ror:2 row_mask:0xf bank_mask:0xf
	v_mov_b32_dpp v236, v218 row_ror:1 row_mask:0xf bank_mask:0xf
	v_mov_b32_dpp v238, v218 row_ror:2 row_mask:0xf bank_mask:0xf
	v_mov_b32_dpp v185, v148 row_ror:1 row_mask:0xf bank_mask:0xf
	v_mov_b32_dpp v199, v148 row_ror:2 row_mask:0xf bank_mask:0xf
	v_mov_b32_dpp v212, v149 row_ror:1 row_mask:0xf bank_mask:0xf
	v_mov_b32_dpp v215, v149 row_ror:2 row_mask:0xf bank_mask:0xf
	v_mov_b32_dpp v219, v150 row_ror:1 row_mask:0xf bank_mask:0xf
	v_mov_b32_dpp v237, v150 row_ror:2 row_mask:0xf bank_mask:0xf
	v_mov_b32_dpp v218, v151 row_ror:1 row_mask:0xf bank_mask:0xf
	v_mov_b32_dpp v239, v217 row_ror:1 row_mask:0xf bank_mask:0xf
	v_mov_b32_dpp v240, v151 row_ror:2 row_mask:0xf bank_mask:0xf
	v_mov_b32_dpp v241, v217 row_ror:2 row_mask:0xf bank_mask:0xf
	s_and_saveexec_b64 s[16:17], s[60:61]
	s_xor_b64 s[18:19], exec, s[16:17]
	s_cbranch_execz .LBB0_797
	v_cndmask_b32_e64 v190, v231, v229, s[8:9]
	v_cndmask_b32_e64 v191, v235, v233, s[8:9]
	v_cndmask_b32_e64 v188, v228, v230, s[6:7]
	v_cndmask_b32_e64 v189, v232, v234, s[6:7]
	v_pk_fma_f32 v[190:191], v[44:45], v[190:191], v[52:53]
	v_cndmask_b32_e64 v198, v185, v198, s[6:7]
	v_pk_fma_f32 v[188:189], v[40:41], v[188:189], v[190:191]
	s_nop 0
	v_pk_fma_f32 v[188:189], v[48:49], v[156:157], v[188:189]
	s_nop 0
	v_mul_f32_e32 v190, 0xbfb8aa3b, v188
	v_mul_f32_e32 v191, 0xbfb8aa3b, v189
	v_exp_f32_e32 v190, v190
	v_exp_f32_e32 v191, v191
	s_nop 0
	v_pk_add_f32 v[190:191], v[190:191], 1.0 op_sel_hi:[1,0]
	s_nop 0
	v_rcp_f32_e32 v228, v191
	s_nop 0
	v_mul_f32_e32 v217, v189, v228
	v_cndmask_b32_e64 v228, v220, v222, s[6:7]
	v_cndmask_b32_e64 v220, v223, v221, s[8:9]
	v_cndmask_b32_e64 v221, v227, v225, s[8:9]
	v_cndmask_b32_e64 v229, v224, v226, s[6:7]
	v_pk_fma_f32 v[220:221], v[46:47], v[220:221], v[54:55]
	v_rcp_f32_e32 v232, v190
	v_pk_fma_f32 v[220:221], v[42:43], v[228:229], v[220:221]
	v_mov_b32_e32 v189, v217
	v_pk_fma_f32 v[220:221], v[50:51], v[158:159], v[220:221]
	v_mul_f32_e32 v222, 0xbfb8aa3b, v220
	v_mul_f32_e32 v223, 0xbfb8aa3b, v221
	v_exp_f32_e32 v222, v222
	v_exp_f32_e32 v223, v223
	s_nop 0
	v_pk_add_f32 v[222:223], v[222:223], 1.0 op_sel_hi:[1,0]
	v_rcp_f32_e32 v225, v223
	v_mul_f32_e32 v188, v188, v232
	v_pk_mul_f32 v[152:153], v[152:153], v[188:189]
	v_cndmask_b32_e64 v190, v238, v237, s[8:9]
	v_cndmask_b32_e64 v191, v241, v240, s[8:9]
	v_rcp_f32_e32 v226, v222
	v_mul_f32_e32 v188, v221, v225
	v_cndmask_b32_e64 v224, v219, v236, s[6:7]
	v_cndmask_b32_e64 v225, v218, v239, s[6:7]
	v_pk_fma_f32 v[190:191], v[74:75], v[190:191], v[78:79]
	v_mov_b32_e32 v189, v188
	v_pk_fma_f32 v[190:191], v[66:67], v[224:225], v[190:191]
	v_pk_fma_f32 v[190:191], v[70:71], v[150:151], v[190:191]
	v_mul_f32_e32 v218, 0xbfb8aa3b, v190
	v_mul_f32_e32 v219, 0xbfb8aa3b, v191
	v_exp_f32_e32 v218, v218
	v_exp_f32_e32 v219, v219
	s_nop 0
	v_pk_add_f32 v[218:219], v[218:219], 1.0 op_sel_hi:[1,0]
	v_rcp_f32_e32 v223, v219
	v_mul_f32_e32 v188, v220, v226
	v_pk_mul_f32 v[154:155], v[154:155], v[188:189]
	v_cndmask_b32_e64 v220, v213, v199, s[8:9]
	v_cndmask_b32_e64 v221, v216, v215, s[8:9]
	v_cndmask_b32_e64 v199, v212, v214, s[6:7]
	v_pk_fma_f32 v[212:213], v[72:73], v[220:221], v[76:77]
	v_pk_fma_f32 v[198:199], v[64:65], v[198:199], v[212:213]
	v_pk_fma_f32 v[198:199], v[68:69], v[148:149], v[198:199]
	v_rcp_f32_e32 v222, v218
	v_mul_f32_e32 v185, 0xbfb8aa3b, v198
	v_exp_f32_e32 v212, v185
	v_mul_f32_e32 v185, 0xbfb8aa3b, v199
	v_exp_f32_e32 v213, v185
	v_mul_f32_e32 v189, v191, v223
	v_pk_add_f32 v[212:213], v[212:213], 1.0 op_sel_hi:[1,0]
	v_rcp_f32_e32 v215, v213
	v_mul_f32_e32 v188, v190, v222
	v_pk_mul_f32 v[188:189], v[146:147], v[188:189]
	v_rcp_f32_e32 v190, v212
	v_mul_f32_e32 v147, v199, v215
	v_mul_f32_e32 v146, v198, v190
	v_pk_mul_f32 v[146:147], v[144:145], v[146:147]
	v_cvt_pk_bf16_f32 v144, v152, v153
	v_mov_b64_e32 v[152:153], s[44:45]
	v_mad_i64_i32 v[152:153], s[16:17], v184, s33, v[152:153]
	v_cvt_pk_bf16_f32 v145, v154, v155
	v_cvt_pk_bf16_f32 v146, v146, v147
	v_cvt_pk_bf16_f32 v147, v188, v189
	v_lshl_add_u64 v[152:153], v[180:181], 1, v[152:153]
	global_store_dwordx4 v[152:153], v[144:147], off

; __device__ __forceinline__ unsigned pk2(float lo, float hi) { f32x2_t v = {lo, hi}; bf16x2_t b = __builtin_convertvector(v, bf16x2_t); return __builtin_bit_cast(unsigned, b); }
; __device__ __forceinline__ float dpp_ror1(float x) { return __int_as_float(__builtin_amdgcn_update_dpp(0, __float_as_int(x), 0x121, 0xf, 0xf, false)); }
; __device__ __forceinline__ float dpp_ror2(float x) { return __int_as_float(__builtin_amdgcn_update_dpp(0, __float_as_int(x), 0x122, 0xf, 0xf, false)); }
;     __device__ __forceinline__ void operator()(const f32x4 (&acc)[2][2][4][2], const Unit& u, int wr, int wc, int fr, int fq) const {
;     ...
;             for (int m = 0; m < 4; ++m) { const int row = rowb + ai * HALF + m * 16; const float rs = rsq(row);
;                 f32x4 g[2], a[2];
; #pragma unroll
;                 for (int n = 0; n < 2; ++n) { g[n] = acc[ai][0][m][n] * rs; const f32x4 up = acc[ai][1][m][n] * rs;
; #pragma unroll
;                     for (int e = 0; e < 4; ++e) { const float r1c = dpp_ror1(g[n][e]), r1p = dpp_ror1(gprev[n][e]), r2c = dpp_ror2(g[n][e]), r2p = dpp_ror2(gprev[n][e]);
;                         const float p1 = fr >= 1 ? r1c : r1p, p2 = fr >= 2 ? r2c : r2p;
;                         const float c = bb[n][e] + w0[n][e] * p2 + w1[n][e] * p1 + w2[n][e] * g[n][e]; a[n][e] = c / (1.f + __expf(-c)) * up[e]; }
;                     if (ai == 0 && m == 0 && wr == 0 && fr < 2) { *(f32x4*)(firstg + ((size_t)u.pm * 2 + fr) * FF + ch0 + 4 * n) = g[n]; *(f32x4*)(firstup + ((size_t)u.pm * 2 + fr) * FF + ch0 + 4 * n) = up; }
;                     if (ai == 1 && m == 3 && wr == 1 && fr >= 14) *(f32x4*)(lastg + ((size_t)u.pm * 2 + (fr - 14)) * FF + ch0 + 4 * n) = g[n]; }
;                 if (!(ai == 0 && m == 0 && wr == 0 && fr < 2)) { u32x4 w; w.x = pk2(a[0][0], a[0][1]); w.y = pk2(a[0][2], a[0][3]); w.z = pk2(a[1][0], a[1][1]); w.w = pk2(a[1][2], a[1][3]);
;                     *(u32x4*)(ACT + (size_t)row * FF + ch0) = w; }
;                 gprev[0] = g[0]; gprev[1] = g[1]; }
.LBB0_799:
	s_or_b64 exec, exec, s[18:19]
	s_nop 0
	v_or_b32_e32 v144, 16, v184
	v_ashrrev_i32_e32 v145, 31, v144
	v_lshlrev_b64 v[146:147], 5, v[144:145]
	v_lshl_add_u64 v[146:147], s[46:47], 0, v[146:147]
	global_load_dwordx4 v[152:155], v[146:147], off
	global_load_dwordx4 v[188:191], v[146:147], off offset:16
	v_mov_b32_dpp v199, v156 row_ror:2 row_mask:0xf bank_mask:0xf
	v_mov_b32_dpp v215, v157 row_ror:2 row_mask:0xf bank_mask:0xf
	v_mov_b32_dpp v185, v156 row_ror:1 row_mask:0xf bank_mask:0xf
	v_mov_b32_dpp v213, v157 row_ror:1 row_mask:0xf bank_mask:0xf
	v_mov_b32_dpp v219, v158 row_ror:2 row_mask:0xf bank_mask:0xf
	v_mov_b32_dpp v223, v159 row_ror:2 row_mask:0xf bank_mask:0xf
	v_mov_b32_dpp v217, v158 row_ror:1 row_mask:0xf bank_mask:0xf
	v_mov_b32_dpp v221, v159 row_ror:1 row_mask:0xf bank_mask:0xf
	s_waitcnt vmcnt(1)
	v_mov_b32_e32 v146, v153
	v_mov_b32_e32 v147, v154
	v_mov_b32_e32 v153, v155
	s_waitcnt vmcnt(0)
	v_mov_b32_e32 v154, v190
	v_mov_b32_e32 v155, v188
	v_mov_b32_e32 v188, v191
	v_pk_add_f32 v[146:147], v[146:147], v[152:153]
	v_pk_add_f32 v[152:153], v[154:155], v[188:189]
	v_add_f32_e32 v146, v146, v147
	v_add_f32_e32 v146, v146, v153
	v_add_f32_e32 v146, v152, v146
	v_fmamk_f32 v146, v146, 0x3a000000, v178
	v_mul_f32_e32 v147, 0x4b800000, v146
	v_cmp_gt_f32_e32 vcc, s96, v146
	s_nop 1
	v_cndmask_b32_e32 v146, v146, v147, vcc
	v_rsq_f32_e32 v146, v146
	s_nop 0
	v_mul_f32_e32 v147, 0x45800000, v146
	v_cndmask_b32_e32 v146, v146, v147, vcc
	v_pk_mul_f32 v[140:141], v[140:141], v[146:147] op_sel_hi:[1,0]
	v_pk_mul_f32 v[142:143], v[142:143], v[146:147] op_sel_hi:[1,0]
	s_nop 0
	v_mov_b32_dpp v198, v140 row_ror:2 row_mask:0xf bank_mask:0xf
	v_mov_b32_dpp v214, v141 row_ror:2 row_mask:0xf bank_mask:0xf
	v_mov_b32_dpp v145, v140 row_ror:1 row_mask:0xf bank_mask:0xf
	v_mov_b32_dpp v212, v141 row_ror:1 row_mask:0xf bank_mask:0xf
	v_cndmask_b32_e64 v155, v215, v214, s[8:9]
	v_cndmask_b32_e64 v154, v199, v198, s[8:9]
	v_cndmask_b32_e64 v153, v212, v213, s[6:7]
	v_cndmask_b32_e64 v152, v145, v185, s[6:7]
	v_pk_fma_f32 v[154:155], v[44:45], v[154:155], v[52:53]
	v_mov_b32_dpp v218, v142 row_ror:2 row_mask:0xf bank_mask:0xf
	v_pk_fma_f32 v[152:153], v[40:41], v[152:153], v[154:155]
	v_mov_b32_dpp v222, v143 row_ror:2 row_mask:0xf bank_mask:0xf
	v_pk_fma_f32 v[140:141], v[48:49], v[140:141], v[152:153]
	v_mov_b32_dpp v216, v142 row_ror:1 row_mask:0xf bank_mask:0xf
	v_mul_f32_e32 v147, 0xbfb8aa3b, v140
	v_mul_f32_e32 v153, 0xbfb8aa3b, v141
	v_exp_f32_e32 v152, v147
	v_exp_f32_e32 v153, v153
	v_mov_b32_dpp v220, v143 row_ror:1 row_mask:0xf bank_mask:0xf
	v_cndmask_b32_e64 v159, v223, v222, s[8:9]
	v_cndmask_b32_e64 v158, v219, v218, s[8:9]
	v_cndmask_b32_e64 v157, v220, v221, s[6:7]
	v_cndmask_b32_e64 v156, v216, v217, s[6:7]
	v_pk_fma_f32 v[158:159], v[46:47], v[158:159], v[54:55]
	v_pk_add_f32 v[152:153], v[152:153], 1.0 op_sel_hi:[1,0]
	v_pk_fma_f32 v[154:155], v[42:43], v[156:157], v[158:159]
	v_pk_mul_f32 v[138:139], v[138:139], v[146:147] op_sel_hi:[1,0]
	v_pk_fma_f32 v[142:143], v[50:51], v[142:143], v[154:155]
	v_pk_mul_f32 v[136:137], v[136:137], v[146:147] op_sel_hi:[1,0]
	v_mul_f32_e32 v154, 0xbfb8aa3b, v142
	v_mul_f32_e32 v155, 0xbfb8aa3b, v143
	v_rcp_f32_e32 v185, v153
	v_exp_f32_e32 v154, v154
	v_exp_f32_e32 v155, v155
	v_rcp_f32_e32 v188, v152
	v_pk_add_f32 v[154:155], v[154:155], 1.0 op_sel_hi:[1,0]
	v_rcp_f32_e32 v189, v155
	v_mul_f32_e32 v141, v141, v185
	v_mul_f32_e32 v140, v140, v188
	v_pk_mul_f32 v[136:137], v[136:137], v[140:141]
	v_rcp_f32_e32 v147, v154
	v_mul_f32_e32 v141, v143, v189
	v_pk_mul_f32 v[132:133], v[132:133], v[146:147] op_sel_hi:[1,0]
	v_mov_b32_dpp v143, v148 row_ror:1 row_mask:0xf bank_mask:0xf
	s_nop 0
	v_mov_b32_dpp v157, v132 row_ror:2 row_mask:0xf bank_mask:0xf
	v_mov_b32_dpp v152, v148 row_ror:2 row_mask:0xf bank_mask:0xf
	v_mov_b32_dpp v159, v133 row_ror:2 row_mask:0xf bank_mask:0xf
	v_mov_b32_dpp v153, v149 row_ror:2 row_mask:0xf bank_mask:0xf
	v_mov_b32_dpp v156, v132 row_ror:1 row_mask:0xf bank_mask:0xf
	v_mov_b32_dpp v158, v133 row_ror:1 row_mask:0xf bank_mask:0xf
	v_mov_b32_dpp v148, v149 row_ror:1 row_mask:0xf bank_mask:0xf
	v_cndmask_b32_e64 v153, v153, v159, s[8:9]
	v_cndmask_b32_e64 v152, v152, v157, s[8:9]
	v_cndmask_b32_e64 v149, v158, v148, s[6:7]
	v_cndmask_b32_e64 v148, v156, v143, s[6:7]
	v_pk_fma_f32 v[152:153], v[72:73], v[152:153], v[76:77]
	v_pk_fma_f32 v[148:149], v[64:65], v[148:149], v[152:153]
	v_mul_f32_e32 v140, v142, v147
	v_pk_fma_f32 v[132:133], v[68:69], v[132:133], v[148:149]
	v_pk_mul_f32 v[138:139], v[138:139], v[140:141]
	v_mul_f32_e32 v143, 0xbfb8aa3b, v132
	v_exp_f32_e32 v148, v143
	v_mul_f32_e32 v143, 0xbfb8aa3b, v133
	v_exp_f32_e32 v149, v143
	v_pk_mul_f32 v[134:135], v[134:135], v[146:147] op_sel_hi:[1,0]
	v_pk_mul_f32 v[130:131], v[130:131], v[146:147] op_sel_hi:[1,0]
	v_pk_mul_f32 v[128:129], v[128:129], v[146:147] op_sel_hi:[1,0]
	v_pk_add_f32 v[140:141], v[148:149], 1.0 op_sel_hi:[1,0]
	v_rcp_f32_e32 v143, v141
	v_mov_b32_dpp v154, v134 row_ror:2 row_mask:0xf bank_mask:0xf
	v_mul_f32_e32 v133, v133, v143
	v_mov_b32_dpp v142, v150 row_ror:1 row_mask:0xf bank_mask:0xf
	v_mov_b32_dpp v146, v150 row_ror:2 row_mask:0xf bank_mask:0xf
	v_mov_b32_dpp v155, v135 row_ror:2 row_mask:0xf bank_mask:0xf
	v_mov_b32_dpp v147, v151 row_ror:2 row_mask:0xf bank_mask:0xf
	v_mov_b32_dpp v153, v134 row_ror:1 row_mask:0xf bank_mask:0xf
	v_mov_b32_dpp v150, v135 row_ror:1 row_mask:0xf bank_mask:0xf
	v_mov_b32_dpp v143, v151 row_ror:1 row_mask:0xf bank_mask:0xf
	v_cndmask_b32_e64 v147, v147, v155, s[8:9]
	v_cndmask_b32_e64 v146, v146, v154, s[8:9]
	v_cndmask_b32_e64 v143, v150, v143, s[6:7]
	v_cndmask_b32_e64 v142, v153, v142, s[6:7]
	v_pk_fma_f32 v[146:147], v[74:75], v[146:147], v[78:79]
	v_rcp_f32_e32 v149, v140
	v_pk_fma_f32 v[142:143], v[66:67], v[142:143], v[146:147]
	v_pk_fma_f32 v[134:135], v[70:71], v[134:135], v[142:143]
	v_mul_f32_e32 v142, 0xbfb8aa3b, v134
	v_mul_f32_e32 v143, 0xbfb8aa3b, v135
	v_exp_f32_e32 v142, v142
	v_exp_f32_e32 v143, v143
	s_nop 0
	v_pk_add_f32 v[142:143], v[142:143], 1.0 op_sel_hi:[1,0]
	v_rcp_f32_e32 v147, v143
	v_mul_f32_e32 v132, v132, v149
	v_pk_mul_f32 v[128:129], v[128:129], v[132:133]
	v_rcp_f32_e32 v141, v142
	v_mul_f32_e32 v133, v135, v147
	v_mul_f32_e32 v132, v134, v141
	v_pk_mul_f32 v[130:131], v[130:131], v[132:133]
	v_cvt_pk_bf16_f32 v134, v128, v129
	v_mov_b64_e32 v[128:129], s[44:45]
	v_cvt_pk_bf16_f32 v132, v136, v137
	v_cvt_pk_bf16_f32 v135, v130, v131
	v_mad_i64_i32 v[136:137], s[16:17], v144, s33, v[128:129]
	v_lshlrev_b64 v[130:131], 1, v[180:181]
	v_cvt_pk_bf16_f32 v133, v138, v139
	v_lshl_add_u64 v[136:137], v[136:137], 0, v[130:131]
	global_store_dwordx4 v[136:137], v[132:135], off
	s_nop 1
	v_or_b32_e32 v132, 32, v184
	s_nop 0
	v_ashrrev_i32_e32 v133, 31, v132
	v_lshlrev_b64 v[134:135], 5, v[132:133]
	v_lshl_add_u64 v[138:139], s[46:47], 0, v[134:135]
	global_load_dwordx4 v[134:137], v[138:139], off
	s_nop 0
	global_load_dwordx4 v[138:141], v[138:139], off offset:16
	s_waitcnt vmcnt(1)
; __device__ __forceinline__ unsigned pk2(float lo, float hi) { f32x2_t v = {lo, hi}; bf16x2_t b = __builtin_convertvector(v, bf16x2_t); return __builtin_bit_cast(unsigned, b); }
; __device__ __forceinline__ float dpp_ror1(float x) { return __int_as_float(__builtin_amdgcn_update_dpp(0, __float_as_int(x), 0x121, 0xf, 0xf, false)); }
; __device__ __forceinline__ float dpp_ror2(float x) { return __int_as_float(__builtin_amdgcn_update_dpp(0, __float_as_int(x), 0x122, 0xf, 0xf, false)); }
;     __device__ __forceinline__ void operator()(const f32x4 (&acc)[2][2][4][2], const Unit& u, int wr, int wc, int fr, int fq) const {
;     ...
;             for (int m = 0; m < 4; ++m) { const int row = rowb + ai * HALF + m * 16; const float rs = rsq(row);
;                 f32x4 g[2], a[2];
; #pragma unroll
;                 for (int n = 0; n < 2; ++n) { g[n] = acc[ai][0][m][n] * rs; const f32x4 up = acc[ai][1][m][n] * rs;
; #pragma unroll
;                     for (int e = 0; e < 4; ++e) { const float r1c = dpp_ror1(g[n][e]), r1p = dpp_ror1(gprev[n][e]), r2c = dpp_ror2(g[n][e]), r2p = dpp_ror2(gprev[n][e]);
;                         const float p1 = fr >= 1 ? r1c : r1p, p2 = fr >= 2 ? r2c : r2p;
;                         const float c = bb[n][e] + w0[n][e] * p2 + w1[n][e] * p1 + w2[n][e] * g[n][e]; a[n][e] = c / (1.f + __expf(-c)) * up[e]; }
;                     if (ai == 0 && m == 0 && wr == 0 && fr < 2) { *(f32x4*)(firstg + ((size_t)u.pm * 2 + fr) * FF + ch0 + 4 * n) = g[n]; *(f32x4*)(firstup + ((size_t)u.pm * 2 + fr) * FF + ch0 + 4 * n) = up; }
;                     if (ai == 1 && m == 3 && wr == 1 && fr >= 14) *(f32x4*)(lastg + ((size_t)u.pm * 2 + (fr - 14)) * FF + ch0 + 4 * n) = g[n]; }
;                 if (!(ai == 0 && m == 0 && wr == 0 && fr < 2)) { u32x4 w; w.x = pk2(a[0][0], a[0][1]); w.y = pk2(a[0][2], a[0][3]); w.z = pk2(a[1][0], a[1][1]); w.w = pk2(a[1][2], a[1][3]);
;                     *(u32x4*)(ACT + (size_t)row * FF + ch0) = w; }
;                 gprev[0] = g[0]; gprev[1] = g[1]; }
	v_mov_b32_e32 v142, v135
	v_mov_b32_e32 v143, v136
	v_mov_b32_e32 v135, v137
	v_pk_add_f32 v[134:135], v[142:143], v[134:135]
	s_waitcnt vmcnt(0)
	v_mov_b32_e32 v136, v140
	v_mov_b32_e32 v137, v138
	v_mov_b32_e32 v138, v141
	v_pk_add_f32 v[136:137], v[136:137], v[138:139]
	v_add_f32_e32 v133, v134, v135
	v_add_f32_e32 v133, v133, v137
	v_add_f32_e32 v133, v136, v133
	v_fmamk_f32 v133, v133, 0x3a000000, v178
	v_mul_f32_e32 v134, 0x4b800000, v133
	v_cmp_gt_f32_e32 vcc, s96, v133
	s_nop 1
	v_cndmask_b32_e32 v133, v133, v134, vcc
	v_rsq_f32_e32 v133, v133
	s_nop 0
	v_mul_f32_e32 v134, 0x45800000, v133
	v_cndmask_b32_e32 v134, v133, v134, vcc
	v_pk_mul_f32 v[124:125], v[124:125], v[134:135] op_sel_hi:[1,0]
	s_nop 0
	s_nop 0
	v_mov_b32_dpp v142, v124 row_ror:2 row_mask:0xf bank_mask:0xf
	v_mov_b32_dpp v144, v125 row_ror:2 row_mask:0xf bank_mask:0xf
	v_mov_b32_dpp v133, v124 row_ror:1 row_mask:0xf bank_mask:0xf
	v_mov_b32_dpp v143, v125 row_ror:1 row_mask:0xf bank_mask:0xf
	v_cndmask_b32_e64 v139, v214, v144, s[8:9]
	v_cndmask_b32_e64 v138, v198, v142, s[8:9]
	v_cndmask_b32_e64 v137, v143, v212, s[6:7]
	v_cndmask_b32_e64 v136, v133, v145, s[6:7]
	v_pk_fma_f32 v[138:139], v[44:45], v[138:139], v[52:53]
	s_nop 0
	v_pk_fma_f32 v[136:137], v[40:41], v[136:137], v[138:139]
	s_nop 0
	v_pk_fma_f32 v[124:125], v[48:49], v[124:125], v[136:137]
	s_nop 0
	v_mul_f32_e32 v135, 0xbfb8aa3b, v124
	v_exp_f32_e32 v136, v135
	v_mul_f32_e32 v135, 0xbfb8aa3b, v125
	v_exp_f32_e32 v137, v135
	s_nop 0
	v_pk_add_f32 v[136:137], v[136:137], 1.0 op_sel_hi:[1,0]
	s_nop 0
	v_rcp_f32_e32 v138, v137
	v_pk_mul_f32 v[126:127], v[126:127], v[134:135] op_sel_hi:[1,0]
	v_pk_mul_f32 v[122:123], v[122:123], v[134:135] op_sel_hi:[1,0]
	v_pk_mul_f32 v[120:121], v[120:121], v[134:135] op_sel_hi:[1,0]
	v_mov_b32_dpp v148, v126 row_ror:2 row_mask:0xf bank_mask:0xf
	v_mov_b32_dpp v151, v127 row_ror:2 row_mask:0xf bank_mask:0xf
	v_mul_f32_e32 v135, v125, v138
	v_mov_b32_dpp v147, v126 row_ror:1 row_mask:0xf bank_mask:0xf
	v_mov_b32_dpp v149, v127 row_ror:1 row_mask:0xf bank_mask:0xf
	v_cndmask_b32_e64 v141, v222, v151, s[8:9]
	v_cndmask_b32_e64 v140, v218, v148, s[8:9]
	v_cndmask_b32_e64 v139, v149, v220, s[6:7]
	v_cndmask_b32_e64 v138, v147, v216, s[6:7]
	v_pk_fma_f32 v[140:141], v[46:47], v[140:141], v[54:55]
	v_rcp_f32_e32 v146, v136
	v_pk_fma_f32 v[138:139], v[42:43], v[138:139], v[140:141]
	v_mov_b32_e32 v125, v135
	v_pk_fma_f32 v[126:127], v[50:51], v[126:127], v[138:139]
	v_mul_f32_e32 v138, 0xbfb8aa3b, v126
	v_mul_f32_e32 v139, 0xbfb8aa3b, v127
	v_exp_f32_e32 v138, v138
	v_exp_f32_e32 v139, v139
	s_nop 0
	v_pk_add_f32 v[138:139], v[138:139], 1.0 op_sel_hi:[1,0]
	v_rcp_f32_e32 v141, v139
	v_mul_f32_e32 v124, v124, v146
	v_pk_mul_f32 v[120:121], v[120:121], v[124:125]
	v_rcp_f32_e32 v145, v138
	v_mul_f32_e32 v125, v127, v141
	v_pk_mul_f32 v[116:117], v[116:117], v[134:135] op_sel_hi:[1,0]
	s_nop 0
	s_nop 0
	v_mov_b32_dpp v146, v116 row_ror:2 row_mask:0xf bank_mask:0xf
	v_mov_b32_dpp v185, v117 row_ror:2 row_mask:0xf bank_mask:0xf
	v_mov_b32_dpp v139, v116 row_ror:1 row_mask:0xf bank_mask:0xf
	v_mov_b32_dpp v152, v117 row_ror:1 row_mask:0xf bank_mask:0xf
	v_cndmask_b32_e64 v141, v159, v185, s[8:9]
	v_cndmask_b32_e64 v140, v157, v146, s[8:9]
	v_cndmask_b32_e64 v137, v152, v158, s[6:7]
	v_cndmask_b32_e64 v136, v139, v156, s[6:7]
	v_pk_fma_f32 v[140:141], v[72:73], v[140:141], v[76:77]
	v_pk_fma_f32 v[136:137], v[64:65], v[136:137], v[140:141]
	v_pk_fma_f32 v[116:117], v[68:69], v[116:117], v[136:137]
	v_mul_f32_e32 v124, v126, v145
	v_mul_f32_e32 v135, 0xbfb8aa3b, v116
	v_exp_f32_e32 v136, v135
	v_mul_f32_e32 v135, 0xbfb8aa3b, v117
	v_exp_f32_e32 v137, v135
	v_pk_mul_f32 v[122:123], v[122:123], v[124:125]
	v_pk_mul_f32 v[118:119], v[118:119], v[134:135] op_sel_hi:[1,0]
	v_pk_mul_f32 v[114:115], v[114:115], v[134:135] op_sel_hi:[1,0]
	v_pk_add_f32 v[124:125], v[136:137], 1.0 op_sel_hi:[1,0]
	v_pk_mul_f32 v[112:113], v[112:113], v[134:135] op_sel_hi:[1,0]
	v_rcp_f32_e32 v127, v125
	v_mov_b32_dpp v141, v118 row_ror:2 row_mask:0xf bank_mask:0xf
	v_mov_b32_dpp v156, v119 row_ror:2 row_mask:0xf bank_mask:0xf
	v_mov_b32_dpp v140, v118 row_ror:1 row_mask:0xf bank_mask:0xf
	v_mov_b32_dpp v145, v119 row_ror:1 row_mask:0xf bank_mask:0xf
	v_cndmask_b32_e64 v135, v155, v156, s[8:9]
	v_cndmask_b32_e64 v134, v154, v141, s[8:9]
	v_mul_f32_e32 v117, v117, v127
	v_cndmask_b32_e64 v127, v145, v150, s[6:7]
	v_cndmask_b32_e64 v126, v140, v153, s[6:7]
	v_pk_fma_f32 v[134:135], v[74:75], v[134:135], v[78:79]
	v_rcp_f32_e32 v137, v124
	v_pk_fma_f32 v[126:127], v[66:67], v[126:127], v[134:135]
	v_pk_fma_f32 v[118:119], v[70:71], v[118:119], v[126:127]
	v_mul_f32_e32 v126, 0xbfb8aa3b, v118
	v_mul_f32_e32 v127, 0xbfb8aa3b, v119
	v_exp_f32_e32 v126, v126
	v_exp_f32_e32 v127, v127
	s_nop 0
	v_pk_add_f32 v[126:127], v[126:127], 1.0 op_sel_hi:[1,0]
	v_rcp_f32_e32 v135, v127
	v_mul_f32_e32 v116, v116, v137
	v_pk_mul_f32 v[116:117], v[112:113], v[116:117]
	v_rcp_f32_e32 v125, v126
	v_mul_f32_e32 v113, v119, v135
	v_mul_f32_e32 v112, v118, v125
	v_pk_mul_f32 v[118:119], v[114:115], v[112:113]
	v_cvt_pk_bf16_f32 v114, v116, v117
	v_mad_i64_i32 v[116:117], s[16:17], v132, s33, v[128:129]
	v_cvt_pk_bf16_f32 v112, v120, v121
	v_cvt_pk_bf16_f32 v113, v122, v123
	v_cvt_pk_bf16_f32 v115, v118, v119
	v_lshl_add_u64 v[116:117], v[116:117], 0, v[130:131]
	global_store_dwordx4 v[116:117], v[112:115], off
	s_nop 1
	v_lshlrev_b64 v[112:113], 5, v[186:187]
	v_lshl_add_u64 v[116:117], s[46:47], 0, v[112:113]
	global_load_dwordx4 v[112:115], v[116:117], off
	s_nop 0
	global_load_dwordx4 v[116:119], v[116:117], off offset:16
	s_waitcnt vmcnt(1)
; #define LAS __attribute__((address_space(3)))
; __device__ __forceinline__ unsigned pk2(float lo, float hi) { f32x2_t v = {lo, hi}; bf16x2_t b = __builtin_convertvector(v, bf16x2_t); return __builtin_bit_cast(unsigned, b); }
; __device__ __forceinline__ float dpp_ror1(float x) { return __int_as_float(__builtin_amdgcn_update_dpp(0, __float_as_int(x), 0x121, 0xf, 0xf, false)); }
;     __device__ __forceinline__ void operator()(const f32x4 (&acc)[2][2][4][2], const Unit& u, int wr, int wc, int fr, int fq) const {
;     ...
;             if (wr == 1 || ai == 1) { const int sai = (wr == 1) ? ai : ai - 1, swr = (wr == 1) ? 0 : 1; const LAS float* xp = X + (((sai * 2 + swr) * 4 + wc) * 2) * 32 + 8 * fq;
; #pragma unroll
;                 for (int n = 0; n < 2; ++n) { const f32x4 h2 = *(const LAS f32x4*)(xp + 4 * n), h1 = *(const LAS f32x4*)(xp + 32 + 4 * n); gprev[n] = (fr == 15) ? h1 : h2; } }
;     ...
;             for (int m = 0; m < 4; ++m) { const int row = rowb + ai * HALF + m * 16; const float rs = rsq(row);
;                 f32x4 g[2], a[2];
; #pragma unroll
;                 for (int n = 0; n < 2; ++n) { g[n] = acc[ai][0][m][n] * rs; const f32x4 up = acc[ai][1][m][n] * rs;
; #pragma unroll
;                     for (int e = 0; e < 4; ++e) { const float r1c = dpp_ror1(g[n][e]), r1p = dpp_ror1(gprev[n][e]), r2c = dpp_ror2(g[n][e]), r2p = dpp_ror2(gprev[n][e]);
;                         const float p1 = fr >= 1 ? r1c : r1p, p2 = fr >= 2 ? r2c : r2p;
;                         const float c = bb[n][e] + w0[n][e] * p2 + w1[n][e] * p1 + w2[n][e] * g[n][e]; a[n][e] = c / (1.f + __expf(-c)) * up[e]; }
;                     if (ai == 0 && m == 0 && wr == 0 && fr < 2) { *(f32x4*)(firstg + ((size_t)u.pm * 2 + fr) * FF + ch0 + 4 * n) = g[n]; *(f32x4*)(firstup + ((size_t)u.pm * 2 + fr) * FF + ch0 + 4 * n) = up; }
;                     if (ai == 1 && m == 3 && wr == 1 && fr >= 14) *(f32x4*)(lastg + ((size_t)u.pm * 2 + (fr - 14)) * FF + ch0 + 4 * n) = g[n]; }
;                 if (!(ai == 0 && m == 0 && wr == 0 && fr < 2)) { u32x4 w; w.x = pk2(a[0][0], a[0][1]); w.y = pk2(a[0][2], a[0][3]); w.z = pk2(a[1][0], a[1][1]); w.w = pk2(a[1][2], a[1][3]);
;                     *(u32x4*)(ACT + (size_t)row * FF + ch0) = w; }
;                 gprev[0] = g[0]; gprev[1] = g[1]; }
	v_mov_b32_e32 v120, v113
	v_mov_b32_e32 v121, v114
	v_mov_b32_e32 v113, v115
	v_pk_add_f32 v[112:113], v[120:121], v[112:113]
	s_waitcnt vmcnt(0)
	v_mov_b32_e32 v114, v118
	v_mov_b32_e32 v115, v116
	v_mov_b32_e32 v116, v119
	v_pk_add_f32 v[114:115], v[114:115], v[116:117]
	v_add_f32_e32 v112, v112, v113
	v_add_f32_e32 v112, v112, v115
	v_add_f32_e32 v112, v114, v112
	v_fmamk_f32 v112, v112, 0x3a000000, v178
	v_mul_f32_e32 v113, 0x4b800000, v112
	v_cmp_gt_f32_e32 vcc, s96, v112
	s_nop 1
	v_cndmask_b32_e32 v112, v112, v113, vcc
	v_rsq_f32_e32 v112, v112
	s_nop 0
	v_mul_f32_e32 v113, 0x45800000, v112
	v_cndmask_b32_e32 v112, v112, v113, vcc
	v_pk_mul_f32 v[108:109], v[108:109], v[112:113] op_sel_hi:[1,0]
	s_nop 0
	s_nop 0
	v_mov_b32_dpp v116, v108 row_ror:2 row_mask:0xf bank_mask:0xf
	v_mov_b32_dpp v117, v109 row_ror:2 row_mask:0xf bank_mask:0xf
	v_mov_b32_dpp v113, v108 row_ror:1 row_mask:0xf bank_mask:0xf
	v_mov_b32_dpp v114, v109 row_ror:1 row_mask:0xf bank_mask:0xf
	v_cndmask_b32_e64 v117, v144, v117, s[8:9]
	v_cndmask_b32_e64 v116, v142, v116, s[8:9]
	v_cndmask_b32_e64 v115, v114, v143, s[6:7]
	v_cndmask_b32_e64 v114, v113, v133, s[6:7]
	v_pk_fma_f32 v[116:117], v[44:45], v[116:117], v[52:53]
	s_nop 0
	v_pk_fma_f32 v[114:115], v[40:41], v[114:115], v[116:117]
	s_nop 0
	v_pk_fma_f32 v[108:109], v[48:49], v[108:109], v[114:115]
	s_nop 0
	v_mul_f32_e32 v113, 0xbfb8aa3b, v108
	v_exp_f32_e32 v114, v113
	v_mul_f32_e32 v113, 0xbfb8aa3b, v109
	v_exp_f32_e32 v115, v113
	s_nop 0
	v_pk_add_f32 v[114:115], v[114:115], 1.0 op_sel_hi:[1,0]
	s_nop 0
	v_rcp_f32_e32 v116, v115
	v_pk_mul_f32 v[110:111], v[110:111], v[112:113] op_sel_hi:[1,0]
	v_pk_mul_f32 v[106:107], v[106:107], v[112:113] op_sel_hi:[1,0]
	v_pk_mul_f32 v[104:105], v[104:105], v[112:113] op_sel_hi:[1,0]
	v_mul_f32_e32 v113, v109, v116
	v_mov_b32_dpp v118, v110 row_ror:2 row_mask:0xf bank_mask:0xf
	v_mov_b32_dpp v119, v111 row_ror:2 row_mask:0xf bank_mask:0xf
	v_mov_b32_dpp v116, v110 row_ror:1 row_mask:0xf bank_mask:0xf
	v_mov_b32_dpp v117, v111 row_ror:1 row_mask:0xf bank_mask:0xf
	v_cndmask_b32_e64 v119, v151, v119, s[8:9]
	v_cndmask_b32_e64 v118, v148, v118, s[8:9]
	v_cndmask_b32_e64 v117, v117, v149, s[6:7]
	v_cndmask_b32_e64 v116, v116, v147, s[6:7]
	v_pk_fma_f32 v[118:119], v[46:47], v[118:119], v[54:55]
	v_rcp_f32_e32 v121, v114
	v_pk_fma_f32 v[116:117], v[42:43], v[116:117], v[118:119]
	v_mov_b32_e32 v109, v113
	v_pk_fma_f32 v[110:111], v[50:51], v[110:111], v[116:117]
	v_mul_f32_e32 v116, 0xbfb8aa3b, v110
	v_mul_f32_e32 v117, 0xbfb8aa3b, v111
	v_exp_f32_e32 v116, v116
	v_exp_f32_e32 v117, v117
	s_nop 0
	v_pk_add_f32 v[116:117], v[116:117], 1.0 op_sel_hi:[1,0]
	v_rcp_f32_e32 v119, v117
	v_mul_f32_e32 v108, v108, v121
	v_pk_mul_f32 v[104:105], v[104:105], v[108:109]
	v_rcp_f32_e32 v120, v116
	v_mul_f32_e32 v109, v111, v119
	v_pk_mul_f32 v[100:101], v[100:101], v[112:113] op_sel_hi:[1,0]
	s_nop 1
	v_mov_b32_dpp v117, v100 row_ror:2 row_mask:0xf bank_mask:0xf
	s_nop 0
	v_mov_b32_dpp v118, v101 row_ror:2 row_mask:0xf bank_mask:0xf
	v_mov_b32_dpp v113, v100 row_ror:1 row_mask:0xf bank_mask:0xf
	v_mov_b32_dpp v114, v101 row_ror:1 row_mask:0xf bank_mask:0xf
	v_cndmask_b32_e64 v119, v185, v118, s[8:9]
	v_cndmask_b32_e64 v118, v146, v117, s[8:9]
	v_cndmask_b32_e64 v115, v114, v152, s[6:7]
	v_cndmask_b32_e64 v114, v113, v139, s[6:7]
	v_pk_fma_f32 v[118:119], v[72:73], v[118:119], v[76:77]
	v_pk_fma_f32 v[114:115], v[64:65], v[114:115], v[118:119]
	v_mul_f32_e32 v108, v110, v120
	v_pk_fma_f32 v[100:101], v[68:69], v[100:101], v[114:115]
	v_pk_mul_f32 v[106:107], v[106:107], v[108:109]
	v_mul_f32_e32 v113, 0xbfb8aa3b, v100
	v_exp_f32_e32 v114, v113
	v_mul_f32_e32 v113, 0xbfb8aa3b, v101
	v_exp_f32_e32 v115, v113
	v_pk_mul_f32 v[102:103], v[102:103], v[112:113] op_sel_hi:[1,0]
	v_pk_mul_f32 v[98:99], v[98:99], v[112:113] op_sel_hi:[1,0]
	v_pk_mul_f32 v[96:97], v[96:97], v[112:113] op_sel_hi:[1,0]
	v_pk_add_f32 v[108:109], v[114:115], 1.0 op_sel_hi:[1,0]
	s_nop 0
	v_rcp_f32_e32 v111, v109
	s_nop 0
	v_mul_f32_e32 v101, v101, v111
	v_mov_b32_dpp v112, v102 row_ror:2 row_mask:0xf bank_mask:0xf
	v_mov_b32_dpp v113, v103 row_ror:2 row_mask:0xf bank_mask:0xf
	v_mov_b32_dpp v110, v102 row_ror:1 row_mask:0xf bank_mask:0xf
	v_mov_b32_dpp v111, v103 row_ror:1 row_mask:0xf bank_mask:0xf
	v_cndmask_b32_e64 v113, v156, v113, s[8:9]
	v_cndmask_b32_e64 v112, v141, v112, s[8:9]
	v_cndmask_b32_e64 v111, v111, v145, s[6:7]
	v_cndmask_b32_e64 v110, v110, v140, s[6:7]
	v_pk_fma_f32 v[112:113], v[74:75], v[112:113], v[78:79]
	v_rcp_f32_e32 v115, v108
	v_pk_fma_f32 v[110:111], v[66:67], v[110:111], v[112:113]
	v_pk_fma_f32 v[102:103], v[70:71], v[102:103], v[110:111]
	v_mul_f32_e32 v110, 0xbfb8aa3b, v102
	v_mul_f32_e32 v111, 0xbfb8aa3b, v103
	v_exp_f32_e32 v110, v110
	v_exp_f32_e32 v111, v111
	s_nop 0
	v_pk_add_f32 v[110:111], v[110:111], 1.0 op_sel_hi:[1,0]
	v_rcp_f32_e32 v113, v111
	v_mul_f32_e32 v100, v100, v115
	v_pk_mul_f32 v[100:101], v[96:97], v[100:101]
	v_rcp_f32_e32 v109, v110
	v_mul_f32_e32 v97, v103, v113
	v_mul_f32_e32 v96, v102, v109
	v_pk_mul_f32 v[102:103], v[98:99], v[96:97]
	v_cvt_pk_bf16_f32 v98, v100, v101
	v_mad_i64_i32 v[100:101], s[16:17], v186, s33, v[128:129]
	v_cvt_pk_bf16_f32 v96, v104, v105
	v_cvt_pk_bf16_f32 v97, v106, v107
	v_cvt_pk_bf16_f32 v99, v102, v103
	v_lshl_add_u64 v[100:101], v[100:101], 0, v[130:131]
	global_store_dwordx4 v[100:101], v[96:99], off
	s_nop 1
	v_add_u32_e32 v96, 0x80, v184
	v_ashrrev_i32_e32 v97, 31, v96
	v_lshlrev_b64 v[98:99], 5, v[96:97]
	v_lshl_add_u64 v[102:103], s[46:47], 0, v[98:99]
	global_load_dwordx4 v[98:101], v[102:103], off
	s_nop 0
	global_load_dwordx4 v[102:105], v[102:103], off offset:16
	ds_read_b128 v[106:109], v204 offset:144
	ds_read_b128 v[110:113], v204 offset:16
	ds_read_b128 v[114:117], v204
	ds_read_b128 v[118:121], v204 offset:128
	s_waitcnt lgkmcnt(2)
; #define LAS __attribute__((address_space(3)))
; __device__ __forceinline__ unsigned pk2(float lo, float hi) { f32x2_t v = {lo, hi}; bf16x2_t b = __builtin_convertvector(v, bf16x2_t); return __builtin_bit_cast(unsigned, b); }
; __device__ __forceinline__ float dpp_ror1(float x) { return __int_as_float(__builtin_amdgcn_update_dpp(0, __float_as_int(x), 0x121, 0xf, 0xf, false)); }
;     __device__ __forceinline__ void operator()(const f32x4 (&acc)[2][2][4][2], const Unit& u, int wr, int wc, int fr, int fq) const {
;     ...
;             if (wr == 1 || ai == 1) { const int sai = (wr == 1) ? ai : ai - 1, swr = (wr == 1) ? 0 : 1; const LAS float* xp = X + (((sai * 2 + swr) * 4 + wc) * 2) * 32 + 8 * fq;
; #pragma unroll
;                 for (int n = 0; n < 2; ++n) { const f32x4 h2 = *(const LAS f32x4*)(xp + 4 * n), h1 = *(const LAS f32x4*)(xp + 32 + 4 * n); gprev[n] = (fr == 15) ? h1 : h2; } }
;             else { gprev[0] = (f32x4){0.f, 0.f, 0.f, 0.f}; gprev[1] = gprev[0]; }
; #pragma unroll
;             for (int m = 0; m < 4; ++m) { const int row = rowb + ai * HALF + m * 16; const float rs = rsq(row);
;                 f32x4 g[2], a[2];
; #pragma unroll
;                 for (int n = 0; n < 2; ++n) { g[n] = acc[ai][0][m][n] * rs; const f32x4 up = acc[ai][1][m][n] * rs;
; #pragma unroll
;                     for (int e = 0; e < 4; ++e) { const float r1c = dpp_ror1(g[n][e]), r1p = dpp_ror1(gprev[n][e]), r2c = dpp_ror2(g[n][e]), r2p = dpp_ror2(gprev[n][e]);
;                         const float p1 = fr >= 1 ? r1c : r1p, p2 = fr >= 2 ? r2c : r2p;
;                         const float c = bb[n][e] + w0[n][e] * p2 + w1[n][e] * p1 + w2[n][e] * g[n][e]; a[n][e] = c / (1.f + __expf(-c)) * up[e]; }
;                     if (ai == 0 && m == 0 && wr == 0 && fr < 2) { *(f32x4*)(firstg + ((size_t)u.pm * 2 + fr) * FF + ch0 + 4 * n) = g[n]; *(f32x4*)(firstup + ((size_t)u.pm * 2 + fr) * FF + ch0 + 4 * n) = up; }
;                     if (ai == 1 && m == 3 && wr == 1 && fr >= 14) *(f32x4*)(lastg + ((size_t)u.pm * 2 + (fr - 14)) * FF + ch0 + 4 * n) = g[n]; }
;                 if (!(ai == 0 && m == 0 && wr == 0 && fr < 2)) { u32x4 w; w.x = pk2(a[0][0], a[0][1]); w.y = pk2(a[0][2], a[0][3]); w.z = pk2(a[1][0], a[1][1]); w.w = pk2(a[1][2], a[1][3]);
;                     *(u32x4*)(ACT + (size_t)row * FF + ch0) = w; }
	v_cndmask_b32_e64 v97, v113, v109, s[10:11]
	v_cndmask_b32_e64 v112, v112, v108, s[10:11]
	v_cndmask_b32_e64 v106, v110, v106, s[10:11]
	s_waitcnt vmcnt(1)
	v_mov_b32_e32 v108, v99
	v_mov_b32_e32 v109, v100
	v_mov_b32_e32 v99, v101
	v_pk_add_f32 v[98:99], v[108:109], v[98:99]
	s_waitcnt vmcnt(0)
	v_mov_b32_e32 v100, v104
	v_mov_b32_e32 v101, v102
	v_mov_b32_e32 v102, v105
	v_pk_add_f32 v[100:101], v[100:101], v[102:103]
	v_add_f32_e32 v98, v98, v99
	v_add_f32_e32 v98, v98, v101
	v_add_f32_e32 v98, v100, v98
	v_fmamk_f32 v98, v98, 0x3a000000, v178
	v_mul_f32_e32 v99, 0x4b800000, v98
	v_cmp_gt_f32_e32 vcc, s96, v98
	s_waitcnt lgkmcnt(0)
	v_cndmask_b32_e64 v100, v115, v119, s[10:11]
	v_cndmask_b32_e64 v101, v114, v118, s[10:11]
	v_cndmask_b32_e32 v98, v98, v99, vcc
	v_rsq_f32_e32 v98, v98
	v_cndmask_b32_e64 v99, v111, v107, s[10:11]
	v_mul_f32_e32 v102, 0x45800000, v98
	v_cndmask_b32_e32 v98, v98, v102, vcc
	v_pk_mul_f32 v[92:93], v[92:93], v[98:99] op_sel_hi:[1,0]
	s_nop 1
	v_mov_b32_dpp v107, v92 row_ror:1 row_mask:0xf bank_mask:0xf
	v_mov_b32_dpp v102, v101 row_ror:1 row_mask:0xf bank_mask:0xf
	v_mov_b32_dpp v108, v92 row_ror:2 row_mask:0xf bank_mask:0xf
	v_mov_b32_dpp v104, v101 row_ror:2 row_mask:0xf bank_mask:0xf
	v_mov_b32_dpp v111, v93 row_ror:2 row_mask:0xf bank_mask:0xf
	v_mov_b32_dpp v103, v100 row_ror:2 row_mask:0xf bank_mask:0xf
	v_mov_b32_dpp v109, v93 row_ror:1 row_mask:0xf bank_mask:0xf
	v_mov_b32_dpp v101, v100 row_ror:1 row_mask:0xf bank_mask:0xf
	v_cndmask_b32_e64 v100, v107, v102, s[6:7]
	v_cndmask_b32_e64 v103, v103, v111, s[8:9]
	v_cndmask_b32_e64 v102, v104, v108, s[8:9]
	v_cndmask_b32_e64 v101, v109, v101, s[6:7]
	v_pk_fma_f32 v[102:103], v[44:45], v[102:103], v[52:53]
	v_pk_mul_f32 v[94:95], v[94:95], v[98:99] op_sel_hi:[1,0]
	v_pk_fma_f32 v[100:101], v[40:41], v[100:101], v[102:103]
	v_cndmask_b32_e64 v102, v117, v121, s[10:11]
	v_pk_fma_f32 v[92:93], v[48:49], v[92:93], v[100:101]
	v_cndmask_b32_e64 v103, v116, v120, s[10:11]
	v_mul_f32_e32 v100, 0xbfb8aa3b, v92
	v_mul_f32_e32 v101, 0xbfb8aa3b, v93
	v_exp_f32_e32 v100, v100
	v_exp_f32_e32 v101, v101
	s_nop 0
	v_pk_add_f32 v[100:101], v[100:101], 1.0 op_sel_hi:[1,0]
	v_rcp_f32_e32 v105, v101
	v_mov_b32_dpp v115, v94 row_ror:1 row_mask:0xf bank_mask:0xf
	v_mov_b32_dpp v116, v94 row_ror:2 row_mask:0xf bank_mask:0xf
	v_mov_b32_dpp v117, v103 row_ror:2 row_mask:0xf bank_mask:0xf
	v_mul_f32_e32 v93, v93, v105
	v_mov_b32_dpp v104, v103 row_ror:1 row_mask:0xf bank_mask:0xf
	v_mov_b32_dpp v119, v95 row_ror:2 row_mask:0xf bank_mask:0xf
	v_mov_b32_dpp v105, v102 row_ror:2 row_mask:0xf bank_mask:0xf
	v_mov_b32_dpp v118, v95 row_ror:1 row_mask:0xf bank_mask:0xf
	v_mov_b32_dpp v103, v102 row_ror:1 row_mask:0xf bank_mask:0xf
	v_cndmask_b32_e64 v102, v115, v104, s[6:7]
	v_cndmask_b32_e64 v105, v105, v119, s[8:9]
	v_cndmask_b32_e64 v104, v117, v116, s[8:9]
	v_cndmask_b32_e64 v103, v118, v103, s[6:7]
	v_pk_fma_f32 v[104:105], v[46:47], v[104:105], v[54:55]
	v_rcp_f32_e32 v114, v100
	v_pk_fma_f32 v[102:103], v[42:43], v[102:103], v[104:105]
	v_pk_mul_f32 v[88:89], v[88:89], v[98:99] op_sel_hi:[1,0]
	v_pk_fma_f32 v[94:95], v[50:51], v[94:95], v[102:103]
	v_mul_f32_e32 v102, 0xbfb8aa3b, v94
	v_mul_f32_e32 v103, 0xbfb8aa3b, v95
	v_exp_f32_e32 v102, v102
	v_exp_f32_e32 v103, v103
	s_nop 0
	v_pk_add_f32 v[102:103], v[102:103], 1.0 op_sel_hi:[1,0]
	v_rcp_f32_e32 v105, v103
	v_mul_f32_e32 v92, v92, v114
	v_pk_mul_f32 v[88:89], v[88:89], v[92:93]
	v_rcp_f32_e32 v110, v102
	v_mul_f32_e32 v93, v95, v105
	v_pk_mul_f32 v[84:85], v[84:85], v[98:99] op_sel_hi:[1,0]
	v_mov_b32_dpp v100, v106 row_ror:1 row_mask:0xf bank_mask:0xf
	s_nop 0
	v_mov_b32_dpp v113, v84 row_ror:2 row_mask:0xf bank_mask:0xf
	v_mov_b32_dpp v104, v106 row_ror:2 row_mask:0xf bank_mask:0xf
	v_mov_b32_dpp v114, v85 row_ror:2 row_mask:0xf bank_mask:0xf
	v_mov_b32_dpp v105, v99 row_ror:2 row_mask:0xf bank_mask:0xf
	v_mov_b32_dpp v103, v84 row_ror:1 row_mask:0xf bank_mask:0xf
	v_mov_b32_dpp v106, v85 row_ror:1 row_mask:0xf bank_mask:0xf
	v_mov_b32_dpp v101, v99 row_ror:1 row_mask:0xf bank_mask:0xf
	v_cndmask_b32_e64 v105, v105, v114, s[8:9]
	v_cndmask_b32_e64 v104, v104, v113, s[8:9]
	v_cndmask_b32_e64 v101, v106, v101, s[6:7]
	v_cndmask_b32_e64 v100, v103, v100, s[6:7]
	v_pk_fma_f32 v[104:105], v[72:73], v[104:105], v[76:77]
	v_pk_mul_f32 v[90:91], v[90:91], v[98:99] op_sel_hi:[1,0]
	v_pk_fma_f32 v[100:101], v[64:65], v[100:101], v[104:105]
	v_pk_fma_f32 v[84:85], v[68:69], v[84:85], v[100:101]
	v_mul_f32_e32 v92, v94, v110
	v_mul_f32_e32 v99, 0xbfb8aa3b, v84
	v_exp_f32_e32 v100, v99
	v_mul_f32_e32 v99, 0xbfb8aa3b, v85
	v_exp_f32_e32 v101, v99
	v_pk_mul_f32 v[90:91], v[90:91], v[92:93]
	v_pk_mul_f32 v[86:87], v[86:87], v[98:99] op_sel_hi:[1,0]
	v_pk_mul_f32 v[82:83], v[82:83], v[98:99] op_sel_hi:[1,0]
	v_pk_add_f32 v[92:93], v[100:101], 1.0 op_sel_hi:[1,0]
	v_pk_mul_f32 v[80:81], v[80:81], v[98:99] op_sel_hi:[1,0]
	v_rcp_f32_e32 v95, v93
	s_nop 0
	v_mul_f32_e32 v85, v85, v95
	v_mov_b32_dpp v94, v112 row_ror:1 row_mask:0xf bank_mask:0xf
	v_mov_b32_dpp v98, v112 row_ror:2 row_mask:0xf bank_mask:0xf
	v_mov_b32_dpp v105, v86 row_ror:2 row_mask:0xf bank_mask:0xf
	v_mov_b32_dpp v112, v87 row_ror:2 row_mask:0xf bank_mask:0xf
	v_mov_b32_dpp v99, v97 row_ror:2 row_mask:0xf bank_mask:0xf
	v_mov_b32_dpp v104, v86 row_ror:1 row_mask:0xf bank_mask:0xf
	v_mov_b32_dpp v110, v87 row_ror:1 row_mask:0xf bank_mask:0xf
	v_mov_b32_dpp v95, v97 row_ror:1 row_mask:0xf bank_mask:0xf
	v_cndmask_b32_e64 v99, v99, v112, s[8:9]
	v_cndmask_b32_e64 v98, v98, v105, s[8:9]
	v_cndmask_b32_e64 v95, v110, v95, s[6:7]
	v_cndmask_b32_e64 v94, v104, v94, s[6:7]
	v_pk_fma_f32 v[98:99], v[74:75], v[98:99], v[78:79]
	v_rcp_f32_e32 v101, v92
	v_pk_fma_f32 v[94:95], v[66:67], v[94:95], v[98:99]
	v_pk_fma_f32 v[86:87], v[70:71], v[86:87], v[94:95]
	v_mul_f32_e32 v94, 0xbfb8aa3b, v86
	v_mul_f32_e32 v95, 0xbfb8aa3b, v87
	v_exp_f32_e32 v94, v94
	v_exp_f32_e32 v95, v95
	s_nop 0
	v_pk_add_f32 v[94:95], v[94:95], 1.0 op_sel_hi:[1,0]
	v_rcp_f32_e32 v98, v95
	v_mul_f32_e32 v84, v84, v101
	v_pk_mul_f32 v[84:85], v[80:81], v[84:85]
	v_rcp_f32_e32 v93, v94
	v_mul_f32_e32 v81, v87, v98
	v_mul_f32_e32 v80, v86, v93
	v_pk_mul_f32 v[86:87], v[82:83], v[80:81]
	v_cvt_pk_bf16_f32 v82, v84, v85
	v_mad_i64_i32 v[84:85], s[16:17], v96, s33, v[128:129]
	v_cvt_pk_bf16_f32 v80, v88, v89
	v_cvt_pk_bf16_f32 v81, v90, v91
	v_cvt_pk_bf16_f32 v83, v86, v87
	v_lshl_add_u64 v[84:85], v[84:85], 0, v[130:131]
	global_store_dwordx4 v[84:85], v[80:83], off
	s_nop 1
	v_add_u32_e32 v80, 0x90, v184
	s_nop 0
	v_ashrrev_i32_e32 v81, 31, v80
	v_lshlrev_b64 v[82:83], 5, v[80:81]
	v_lshl_add_u64 v[86:87], s[46:47], 0, v[82:83]
	global_load_dwordx4 v[82:85], v[86:87], off
	s_nop 0
	global_load_dwordx4 v[86:89], v[86:87], off offset:16
	s_waitcnt vmcnt(1)
; __device__ __forceinline__ unsigned pk2(float lo, float hi) { f32x2_t v = {lo, hi}; bf16x2_t b = __builtin_convertvector(v, bf16x2_t); return __builtin_bit_cast(unsigned, b); }
; __device__ __forceinline__ float dpp_ror1(float x) { return __int_as_float(__builtin_amdgcn_update_dpp(0, __float_as_int(x), 0x121, 0xf, 0xf, false)); }
; __device__ __forceinline__ float dpp_ror2(float x) { return __int_as_float(__builtin_amdgcn_update_dpp(0, __float_as_int(x), 0x122, 0xf, 0xf, false)); }
;     __device__ __forceinline__ void operator()(const f32x4 (&acc)[2][2][4][2], const Unit& u, int wr, int wc, int fr, int fq) const {
;     ...
;             for (int m = 0; m < 4; ++m) { const int row = rowb + ai * HALF + m * 16; const float rs = rsq(row);
;                 f32x4 g[2], a[2];
; #pragma unroll
;                 for (int n = 0; n < 2; ++n) { g[n] = acc[ai][0][m][n] * rs; const f32x4 up = acc[ai][1][m][n] * rs;
; #pragma unroll
;                     for (int e = 0; e < 4; ++e) { const float r1c = dpp_ror1(g[n][e]), r1p = dpp_ror1(gprev[n][e]), r2c = dpp_ror2(g[n][e]), r2p = dpp_ror2(gprev[n][e]);
;                         const float p1 = fr >= 1 ? r1c : r1p, p2 = fr >= 2 ? r2c : r2p;
;                         const float c = bb[n][e] + w0[n][e] * p2 + w1[n][e] * p1 + w2[n][e] * g[n][e]; a[n][e] = c / (1.f + __expf(-c)) * up[e]; }
;                     if (ai == 0 && m == 0 && wr == 0 && fr < 2) { *(f32x4*)(firstg + ((size_t)u.pm * 2 + fr) * FF + ch0 + 4 * n) = g[n]; *(f32x4*)(firstup + ((size_t)u.pm * 2 + fr) * FF + ch0 + 4 * n) = up; }
;                     if (ai == 1 && m == 3 && wr == 1 && fr >= 14) *(f32x4*)(lastg + ((size_t)u.pm * 2 + (fr - 14)) * FF + ch0 + 4 * n) = g[n]; }
;                 if (!(ai == 0 && m == 0 && wr == 0 && fr < 2)) { u32x4 w; w.x = pk2(a[0][0], a[0][1]); w.y = pk2(a[0][2], a[0][3]); w.z = pk2(a[1][0], a[1][1]); w.w = pk2(a[1][2], a[1][3]);
;                     *(u32x4*)(ACT + (size_t)row * FF + ch0) = w; }
;                 gprev[0] = g[0]; gprev[1] = g[1]; }
	v_mov_b32_e32 v90, v83
	v_mov_b32_e32 v91, v84
	v_mov_b32_e32 v83, v85
	v_pk_add_f32 v[82:83], v[90:91], v[82:83]
	s_waitcnt vmcnt(0)
	v_mov_b32_e32 v84, v88
	v_mov_b32_e32 v85, v86
	v_mov_b32_e32 v86, v89
	v_pk_add_f32 v[84:85], v[84:85], v[86:87]
	v_add_f32_e32 v81, v82, v83
	v_add_f32_e32 v81, v81, v85
	v_add_f32_e32 v81, v84, v81
	v_fmamk_f32 v81, v81, 0x3a000000, v178
	v_mul_f32_e32 v82, 0x4b800000, v81
	v_cmp_gt_f32_e32 vcc, s96, v81
	s_nop 1
	v_cndmask_b32_e32 v81, v81, v82, vcc
	v_rsq_f32_e32 v81, v81
	s_nop 0
	v_mul_f32_e32 v82, 0x45800000, v81
	v_cndmask_b32_e32 v82, v81, v82, vcc
	v_pk_mul_f32 v[60:61], v[60:61], v[82:83] op_sel_hi:[1,0]
	s_nop 0
	s_nop 0
	v_mov_b32_dpp v90, v60 row_ror:2 row_mask:0xf bank_mask:0xf
	v_mov_b32_dpp v92, v61 row_ror:2 row_mask:0xf bank_mask:0xf
	v_mov_b32_dpp v81, v60 row_ror:1 row_mask:0xf bank_mask:0xf
	v_mov_b32_dpp v91, v61 row_ror:1 row_mask:0xf bank_mask:0xf
	v_cndmask_b32_e64 v87, v111, v92, s[8:9]
	v_cndmask_b32_e64 v86, v108, v90, s[8:9]
	v_cndmask_b32_e64 v85, v91, v109, s[6:7]
	v_cndmask_b32_e64 v84, v81, v107, s[6:7]
	v_pk_fma_f32 v[86:87], v[44:45], v[86:87], v[52:53]
	s_nop 0
	v_pk_fma_f32 v[84:85], v[40:41], v[84:85], v[86:87]
	s_nop 0
	v_pk_fma_f32 v[60:61], v[48:49], v[60:61], v[84:85]
	s_nop 0
	v_mul_f32_e32 v83, 0xbfb8aa3b, v60
	v_exp_f32_e32 v84, v83
	v_mul_f32_e32 v83, 0xbfb8aa3b, v61
	v_exp_f32_e32 v85, v83
	s_nop 0
	v_pk_add_f32 v[84:85], v[84:85], 1.0 op_sel_hi:[1,0]
	s_nop 0
	v_rcp_f32_e32 v86, v85
	v_pk_mul_f32 v[62:63], v[62:63], v[82:83] op_sel_hi:[1,0]
	v_pk_mul_f32 v[58:59], v[58:59], v[82:83] op_sel_hi:[1,0]
	v_pk_mul_f32 v[56:57], v[56:57], v[82:83] op_sel_hi:[1,0]
	v_mov_b32_dpp v96, v62 row_ror:2 row_mask:0xf bank_mask:0xf
	v_mov_b32_dpp v98, v63 row_ror:2 row_mask:0xf bank_mask:0xf
	v_mul_f32_e32 v83, v61, v86
	v_mov_b32_dpp v95, v62 row_ror:1 row_mask:0xf bank_mask:0xf
	v_mov_b32_dpp v97, v63 row_ror:1 row_mask:0xf bank_mask:0xf
	v_cndmask_b32_e64 v89, v119, v98, s[8:9]
	v_cndmask_b32_e64 v88, v116, v96, s[8:9]
	v_cndmask_b32_e64 v87, v97, v118, s[6:7]
	v_cndmask_b32_e64 v86, v95, v115, s[6:7]
	v_pk_fma_f32 v[88:89], v[46:47], v[88:89], v[54:55]
	v_rcp_f32_e32 v94, v84
	v_pk_fma_f32 v[86:87], v[42:43], v[86:87], v[88:89]
	v_mov_b32_e32 v61, v83
	v_pk_fma_f32 v[62:63], v[50:51], v[62:63], v[86:87]
	v_mul_f32_e32 v86, 0xbfb8aa3b, v62
	v_mul_f32_e32 v87, 0xbfb8aa3b, v63
	v_exp_f32_e32 v86, v86
	v_exp_f32_e32 v87, v87
	s_nop 0
	v_pk_add_f32 v[86:87], v[86:87], 1.0 op_sel_hi:[1,0]
	v_rcp_f32_e32 v89, v87
	v_mul_f32_e32 v60, v60, v94
	v_pk_mul_f32 v[56:57], v[56:57], v[60:61]
	v_rcp_f32_e32 v93, v86
	v_mul_f32_e32 v61, v63, v89
	v_pk_mul_f32 v[36:37], v[36:37], v[82:83] op_sel_hi:[1,0]
	s_nop 0
	s_nop 0
	v_mov_b32_dpp v94, v36 row_ror:2 row_mask:0xf bank_mask:0xf
	v_mov_b32_dpp v100, v37 row_ror:2 row_mask:0xf bank_mask:0xf
	v_mov_b32_dpp v87, v36 row_ror:1 row_mask:0xf bank_mask:0xf
	v_mov_b32_dpp v99, v37 row_ror:1 row_mask:0xf bank_mask:0xf
	v_cndmask_b32_e64 v89, v114, v100, s[8:9]
	v_cndmask_b32_e64 v88, v113, v94, s[8:9]
	v_cndmask_b32_e64 v85, v99, v106, s[6:7]
	v_cndmask_b32_e64 v84, v87, v103, s[6:7]
	v_pk_fma_f32 v[88:89], v[72:73], v[88:89], v[76:77]
	v_pk_fma_f32 v[84:85], v[64:65], v[84:85], v[88:89]
	v_pk_fma_f32 v[36:37], v[68:69], v[36:37], v[84:85]
	v_mul_f32_e32 v60, v62, v93
	v_mul_f32_e32 v83, 0xbfb8aa3b, v36
	v_exp_f32_e32 v84, v83
	v_mul_f32_e32 v83, 0xbfb8aa3b, v37
	v_exp_f32_e32 v85, v83
	v_pk_mul_f32 v[58:59], v[58:59], v[60:61]
	v_pk_mul_f32 v[38:39], v[38:39], v[82:83] op_sel_hi:[1,0]
	v_pk_mul_f32 v[34:35], v[34:35], v[82:83] op_sel_hi:[1,0]
	v_pk_add_f32 v[60:61], v[84:85], 1.0 op_sel_hi:[1,0]
	v_pk_mul_f32 v[32:33], v[32:33], v[82:83] op_sel_hi:[1,0]
	v_rcp_f32_e32 v63, v61
	v_mov_b32_dpp v89, v38 row_ror:2 row_mask:0xf bank_mask:0xf
	v_mov_b32_dpp v101, v39 row_ror:2 row_mask:0xf bank_mask:0xf
	v_mov_b32_dpp v88, v38 row_ror:1 row_mask:0xf bank_mask:0xf
	v_mov_b32_dpp v93, v39 row_ror:1 row_mask:0xf bank_mask:0xf
	v_cndmask_b32_e64 v83, v112, v101, s[8:9]
	v_cndmask_b32_e64 v82, v105, v89, s[8:9]
	v_mul_f32_e32 v37, v37, v63
	v_cndmask_b32_e64 v63, v93, v110, s[6:7]
	v_cndmask_b32_e64 v62, v88, v104, s[6:7]
	v_pk_fma_f32 v[82:83], v[74:75], v[82:83], v[78:79]
	v_rcp_f32_e32 v85, v60
	v_pk_fma_f32 v[62:63], v[66:67], v[62:63], v[82:83]
	v_pk_fma_f32 v[38:39], v[70:71], v[38:39], v[62:63]
	v_mul_f32_e32 v62, 0xbfb8aa3b, v38
	v_mul_f32_e32 v63, 0xbfb8aa3b, v39
	v_exp_f32_e32 v62, v62
	v_exp_f32_e32 v63, v63
	s_nop 0
	v_pk_add_f32 v[62:63], v[62:63], 1.0 op_sel_hi:[1,0]
	v_rcp_f32_e32 v83, v63
	v_mul_f32_e32 v36, v36, v85
	v_pk_mul_f32 v[36:37], v[32:33], v[36:37]
	v_rcp_f32_e32 v61, v62
	v_mul_f32_e32 v33, v39, v83
	v_mul_f32_e32 v32, v38, v61
	v_pk_mul_f32 v[38:39], v[34:35], v[32:33]
	v_cvt_pk_bf16_f32 v34, v36, v37
	v_mad_i64_i32 v[36:37], s[16:17], v80, s33, v[128:129]
	v_cvt_pk_bf16_f32 v32, v56, v57
	v_cvt_pk_bf16_f32 v33, v58, v59
	v_cvt_pk_bf16_f32 v35, v38, v39
	v_lshl_add_u64 v[36:37], v[36:37], 0, v[130:131]
	global_store_dwordx4 v[36:37], v[32:35], off
	s_nop 1
	v_add_u32_e32 v32, 0xa0, v184
	v_ashrrev_i32_e32 v33, 31, v32
	v_lshlrev_b64 v[34:35], 5, v[32:33]
	v_lshl_add_u64 v[38:39], s[46:47], 0, v[34:35]
	global_load_dwordx4 v[34:37], v[38:39], off
	global_load_dwordx4 v[56:59], v[38:39], off offset:16
	s_waitcnt vmcnt(1)
	v_mov_b32_e32 v38, v35
	v_mov_b32_e32 v39, v36
	v_mov_b32_e32 v35, v37
	v_pk_add_f32 v[34:35], v[38:39], v[34:35]
	s_waitcnt vmcnt(0)
; __device__ __forceinline__ unsigned pk2(float lo, float hi) { f32x2_t v = {lo, hi}; bf16x2_t b = __builtin_convertvector(v, bf16x2_t); return __builtin_bit_cast(unsigned, b); }
; __device__ __forceinline__ float dpp_ror1(float x) { return __int_as_float(__builtin_amdgcn_update_dpp(0, __float_as_int(x), 0x121, 0xf, 0xf, false)); }
; __device__ __forceinline__ float dpp_ror2(float x) { return __int_as_float(__builtin_amdgcn_update_dpp(0, __float_as_int(x), 0x122, 0xf, 0xf, false)); }
;     __device__ __forceinline__ void operator()(const f32x4 (&acc)[2][2][4][2], const Unit& u, int wr, int wc, int fr, int fq) const {
;     ...
;             for (int m = 0; m < 4; ++m) { const int row = rowb + ai * HALF + m * 16; const float rs = rsq(row);
;                 f32x4 g[2], a[2];
; #pragma unroll
;                 for (int n = 0; n < 2; ++n) { g[n] = acc[ai][0][m][n] * rs; const f32x4 up = acc[ai][1][m][n] * rs;
; #pragma unroll
;                     for (int e = 0; e < 4; ++e) { const float r1c = dpp_ror1(g[n][e]), r1p = dpp_ror1(gprev[n][e]), r2c = dpp_ror2(g[n][e]), r2p = dpp_ror2(gprev[n][e]);
;                         const float p1 = fr >= 1 ? r1c : r1p, p2 = fr >= 2 ? r2c : r2p;
;                         const float c = bb[n][e] + w0[n][e] * p2 + w1[n][e] * p1 + w2[n][e] * g[n][e]; a[n][e] = c / (1.f + __expf(-c)) * up[e]; }
;                     if (ai == 0 && m == 0 && wr == 0 && fr < 2) { *(f32x4*)(firstg + ((size_t)u.pm * 2 + fr) * FF + ch0 + 4 * n) = g[n]; *(f32x4*)(firstup + ((size_t)u.pm * 2 + fr) * FF + ch0 + 4 * n) = up; }
;                     if (ai == 1 && m == 3 && wr == 1 && fr >= 14) *(f32x4*)(lastg + ((size_t)u.pm * 2 + (fr - 14)) * FF + ch0 + 4 * n) = g[n]; }
;                 if (!(ai == 0 && m == 0 && wr == 0 && fr < 2)) { u32x4 w; w.x = pk2(a[0][0], a[0][1]); w.y = pk2(a[0][2], a[0][3]); w.z = pk2(a[1][0], a[1][1]); w.w = pk2(a[1][2], a[1][3]);
;                     *(u32x4*)(ACT + (size_t)row * FF + ch0) = w; }
;                 gprev[0] = g[0]; gprev[1] = g[1]; }
	v_mov_b32_e32 v36, v58
	v_mov_b32_e32 v37, v56
	v_mov_b32_e32 v56, v59
	v_pk_add_f32 v[36:37], v[36:37], v[56:57]
	v_add_f32_e32 v33, v34, v35
	v_add_f32_e32 v33, v33, v37
	v_add_f32_e32 v33, v36, v33
	v_fmamk_f32 v33, v33, 0x3a000000, v178
	v_mul_f32_e32 v34, 0x4b800000, v33
	v_cmp_gt_f32_e32 vcc, s96, v33
	s_nop 1
	v_cndmask_b32_e32 v33, v33, v34, vcc
	v_rsq_f32_e32 v33, v33
	s_nop 0
	v_mul_f32_e32 v34, 0x45800000, v33
	v_cndmask_b32_e32 v36, v33, v34, vcc
	v_pk_mul_f32 v[38:39], v[28:29], v[36:37] op_sel_hi:[1,0]
	s_nop 1
	v_mov_b32_dpp v29, v38 row_ror:2 row_mask:0xf bank_mask:0xf
	s_nop 0
	v_mov_b32_dpp v34, v39 row_ror:2 row_mask:0xf bank_mask:0xf
	v_mov_b32_dpp v28, v38 row_ror:1 row_mask:0xf bank_mask:0xf
	v_mov_b32_dpp v33, v39 row_ror:1 row_mask:0xf bank_mask:0xf
	v_cndmask_b32_e64 v59, v92, v34, s[8:9]
	v_cndmask_b32_e64 v58, v90, v29, s[8:9]
	v_cndmask_b32_e64 v57, v33, v91, s[6:7]
	v_cndmask_b32_e64 v56, v28, v81, s[6:7]
	v_pk_fma_f32 v[58:59], v[44:45], v[58:59], v[52:53]
	s_nop 0
	v_pk_fma_f32 v[56:57], v[40:41], v[56:57], v[58:59]
	s_nop 0
	v_pk_fma_f32 v[38:39], v[48:49], v[38:39], v[56:57]
	s_nop 0
	v_mul_f32_e32 v35, 0xbfb8aa3b, v38
	v_exp_f32_e32 v56, v35
	v_mul_f32_e32 v35, 0xbfb8aa3b, v39
	v_exp_f32_e32 v57, v35
	s_nop 0
	v_pk_add_f32 v[56:57], v[56:57], 1.0 op_sel_hi:[1,0]
	s_nop 0
	v_rcp_f32_e32 v37, v57
	s_nop 0
	v_pk_mul_f32 v[60:61], v[26:27], v[36:37] op_sel_hi:[1,0]
	v_pk_mul_f32 v[58:59], v[30:31], v[36:37] op_sel_hi:[1,0]
	v_pk_mul_f32 v[24:25], v[24:25], v[36:37] op_sel_hi:[1,0]
	v_rcp_f32_e32 v82, v56
	v_mul_f32_e32 v39, v39, v37
	v_mov_b32_dpp v27, v58 row_ror:2 row_mask:0xf bank_mask:0xf
	v_mov_b32_dpp v31, v59 row_ror:2 row_mask:0xf bank_mask:0xf
	v_mov_b32_dpp v26, v58 row_ror:1 row_mask:0xf bank_mask:0xf
	v_mov_b32_dpp v30, v59 row_ror:1 row_mask:0xf bank_mask:0xf
	v_cndmask_b32_e64 v81, v98, v31, s[8:9]
	v_cndmask_b32_e64 v80, v96, v27, s[8:9]
	v_cndmask_b32_e64 v63, v30, v97, s[6:7]
	v_cndmask_b32_e64 v62, v26, v95, s[6:7]
	v_pk_fma_f32 v[80:81], v[46:47], v[80:81], v[54:55]
	v_pk_fma_f32 v[62:63], v[42:43], v[62:63], v[80:81]
	v_pk_fma_f32 v[58:59], v[50:51], v[58:59], v[62:63]
	v_mul_f32_e32 v62, 0xbfb8aa3b, v58
	v_mul_f32_e32 v63, 0xbfb8aa3b, v59
	v_exp_f32_e32 v62, v62
	v_exp_f32_e32 v63, v63
	s_nop 0
	v_pk_add_f32 v[62:63], v[62:63], 1.0 op_sel_hi:[1,0]
	v_mul_f32_e32 v38, v38, v82
	v_rcp_f32_e32 v80, v63
	v_pk_mul_f32 v[24:25], v[24:25], v[38:39]
	v_rcp_f32_e32 v82, v62
	v_mul_f32_e32 v39, v59, v80
	v_pk_mul_f32 v[20:21], v[20:21], v[36:37] op_sel_hi:[1,0]
	s_nop 1
	v_mov_b32_dpp v59, v20 row_ror:2 row_mask:0xf bank_mask:0xf
	s_nop 0
	v_mov_b32_dpp v63, v21 row_ror:2 row_mask:0xf bank_mask:0xf
	v_mov_b32_dpp v37, v20 row_ror:1 row_mask:0xf bank_mask:0xf
	v_mov_b32_dpp v56, v21 row_ror:1 row_mask:0xf bank_mask:0xf
	v_cndmask_b32_e64 v81, v100, v63, s[8:9]
	v_cndmask_b32_e64 v80, v94, v59, s[8:9]
	v_cndmask_b32_e64 v57, v56, v99, s[6:7]
	v_cndmask_b32_e64 v56, v37, v87, s[6:7]
	v_pk_fma_f32 v[80:81], v[72:73], v[80:81], v[76:77]
	v_pk_fma_f32 v[56:57], v[64:65], v[56:57], v[80:81]
	v_mul_f32_e32 v38, v58, v82
	v_pk_fma_f32 v[56:57], v[68:69], v[20:21], v[56:57]
	v_pk_mul_f32 v[38:39], v[60:61], v[38:39]
	v_mul_f32_e32 v37, 0xbfb8aa3b, v56
	v_exp_f32_e32 v80, v37
	v_mul_f32_e32 v37, 0xbfb8aa3b, v57
	v_exp_f32_e32 v81, v37
	s_nop 0
	v_pk_add_f32 v[58:59], v[80:81], 1.0 op_sel_hi:[1,0]
	s_nop 0
	v_rcp_f32_e32 v37, v59
	s_nop 0
	v_pk_mul_f32 v[22:23], v[22:23], v[36:37] op_sel_hi:[1,0]
	v_pk_mul_f32 v[18:19], v[18:19], v[36:37] op_sel_hi:[1,0]
	v_pk_mul_f32 v[16:17], v[16:17], v[36:37] op_sel_hi:[1,0]
	v_mul_f32_e32 v37, v57, v37
	v_mov_b32_dpp v62, v22 row_ror:2 row_mask:0xf bank_mask:0xf
	v_mov_b32_dpp v63, v23 row_ror:2 row_mask:0xf bank_mask:0xf
	v_mov_b32_dpp v59, v22 row_ror:1 row_mask:0xf bank_mask:0xf
	v_mov_b32_dpp v60, v23 row_ror:1 row_mask:0xf bank_mask:0xf
	v_cndmask_b32_e64 v63, v101, v63, s[8:9]
	v_cndmask_b32_e64 v62, v89, v62, s[8:9]
	v_cndmask_b32_e64 v61, v60, v93, s[6:7]
	v_cndmask_b32_e64 v60, v59, v88, s[6:7]
	v_pk_fma_f32 v[62:63], v[74:75], v[62:63], v[78:79]
	v_pk_fma_f32 v[60:61], v[66:67], v[60:61], v[62:63]
	v_rcp_f32_e32 v80, v58
	v_pk_fma_f32 v[60:61], v[70:71], v[22:23], v[60:61]
	v_mul_f32_e32 v59, 0xbfb8aa3b, v60
	v_exp_f32_e32 v62, v59
	v_mul_f32_e32 v59, 0xbfb8aa3b, v61
	v_exp_f32_e32 v63, v59
	s_nop 0
	v_pk_add_f32 v[62:63], v[62:63], 1.0 op_sel_hi:[1,0]
	v_rcp_f32_e32 v81, v63
	v_mul_f32_e32 v36, v56, v80
	v_pk_mul_f32 v[36:37], v[16:17], v[36:37]
	v_rcp_f32_e32 v56, v62
	v_mul_f32_e32 v17, v61, v81
	v_mul_f32_e32 v16, v60, v56
	v_pk_mul_f32 v[56:57], v[18:19], v[16:17]
	v_cvt_pk_bf16_f32 v16, v24, v25
	v_mad_i64_i32 v[24:25], s[16:17], v32, s33, v[128:129]
	v_cvt_pk_bf16_f32 v17, v38, v39
	v_cvt_pk_bf16_f32 v18, v36, v37
	v_cvt_pk_bf16_f32 v19, v56, v57
	v_lshl_add_u64 v[24:25], v[24:25], 0, v[130:131]
	global_store_dwordx4 v[24:25], v[16:19], off
	s_nop 1
	v_lshlrev_b64 v[16:17], 5, v[182:183]
	v_lshl_add_u64 v[24:25], s[46:47], 0, v[16:17]
	global_load_dwordx4 v[16:19], v[24:25], off
	global_load_dwordx4 v[36:39], v[24:25], off offset:16
	v_lshl_add_u64 v[24:25], s[76:77], 0, v[168:169]
	s_waitcnt vmcnt(1)
	v_mov_b32_e32 v56, v17
	v_mov_b32_e32 v57, v18
	v_mov_b32_e32 v17, v19
	v_pk_add_f32 v[16:17], v[56:57], v[16:17]
	s_waitcnt vmcnt(0)
	v_mov_b32_e32 v18, v38
	v_mov_b32_e32 v19, v36
	v_mov_b32_e32 v36, v39
	v_pk_add_f32 v[18:19], v[18:19], v[36:37]
	v_add_f32_e32 v16, v16, v17
	v_add_f32_e32 v16, v16, v19
	v_add_f32_e32 v16, v18, v16
	v_fmamk_f32 v16, v16, 0x3a000000, v178
	v_mul_f32_e32 v17, 0x4b800000, v16
	v_cmp_gt_f32_e32 vcc, s96, v16
	v_mad_u64_u32 v[18:19], s[16:17], v24, s97, 0
	s_nop 0
	v_cndmask_b32_e32 v16, v16, v17, vcc
	v_rsq_f32_e32 v16, v16
	v_mad_i32_i24 v19, v25, s97, v19
	v_mul_f32_e32 v17, 0x45800000, v16
	v_cndmask_b32_e32 v16, v16, v17, vcc
	v_pk_mul_f32 v[14:15], v[14:15], v[16:17] op_sel_hi:[1,0]
	v_pk_mul_f32 v[12:13], v[12:13], v[16:17] op_sel_hi:[1,0]
	v_lshl_add_u64 v[18:19], s[52:53], 0, v[18:19]
	s_nop 0
	v_mov_b32_dpp v32, v12 row_ror:1 row_mask:0xf bank_mask:0xf
	v_mov_b32_dpp v35, v12 row_ror:2 row_mask:0xf bank_mask:0xf
	v_mov_b32_dpp v36, v13 row_ror:1 row_mask:0xf bank_mask:0xf
	v_mov_b32_dpp v37, v13 row_ror:2 row_mask:0xf bank_mask:0xf
	v_mov_b32_dpp v38, v14 row_ror:1 row_mask:0xf bank_mask:0xf
	v_mov_b32_dpp v39, v14 row_ror:2 row_mask:0xf bank_mask:0xf
	v_mov_b32_dpp v56, v15 row_ror:1 row_mask:0xf bank_mask:0xf
	v_mov_b32_dpp v57, v15 row_ror:2 row_mask:0xf bank_mask:0xf
	v_lshl_add_u64 v[24:25], v[180:181], 2, v[18:19]
	s_and_saveexec_b64 s[18:19], s[62:63]
	s_cbranch_execz .LBB0_801
	global_store_dwordx4 v[24:25], v[12:15], off
; __device__ __forceinline__ unsigned pk2(float lo, float hi) { f32x2_t v = {lo, hi}; bf16x2_t b = __builtin_convertvector(v, bf16x2_t); return __builtin_bit_cast(unsigned, b); }
; __device__ __forceinline__ float dpp_ror1(float x) { return __int_as_float(__builtin_amdgcn_update_dpp(0, __float_as_int(x), 0x121, 0xf, 0xf, false)); }
; __device__ __forceinline__ float dpp_ror2(float x) { return __int_as_float(__builtin_amdgcn_update_dpp(0, __float_as_int(x), 0x122, 0xf, 0xf, false)); }
;     __device__ __forceinline__ void operator()(const f32x4 (&acc)[2][2][4][2], const Unit& u, int wr, int wc, int fr, int fq) const {
;     ...
;             for (int m = 0; m < 4; ++m) { const int row = rowb + ai * HALF + m * 16; const float rs = rsq(row);
;                 f32x4 g[2], a[2];
; #pragma unroll
;                 for (int n = 0; n < 2; ++n) { g[n] = acc[ai][0][m][n] * rs; const f32x4 up = acc[ai][1][m][n] * rs;
; #pragma unroll
;                     for (int e = 0; e < 4; ++e) { const float r1c = dpp_ror1(g[n][e]), r1p = dpp_ror1(gprev[n][e]), r2c = dpp_ror2(g[n][e]), r2p = dpp_ror2(gprev[n][e]);
;                         const float p1 = fr >= 1 ? r1c : r1p, p2 = fr >= 2 ? r2c : r2p;
;                         const float c = bb[n][e] + w0[n][e] * p2 + w1[n][e] * p1 + w2[n][e] * g[n][e]; a[n][e] = c / (1.f + __expf(-c)) * up[e]; }
;                     if (ai == 0 && m == 0 && wr == 0 && fr < 2) { *(f32x4*)(firstg + ((size_t)u.pm * 2 + fr) * FF + ch0 + 4 * n) = g[n]; *(f32x4*)(firstup + ((size_t)u.pm * 2 + fr) * FF + ch0 + 4 * n) = up; }
;                     if (ai == 1 && m == 3 && wr == 1 && fr >= 14) *(f32x4*)(lastg + ((size_t)u.pm * 2 + (fr - 14)) * FF + ch0 + 4 * n) = g[n]; }
;                 if (!(ai == 0 && m == 0 && wr == 0 && fr < 2)) { u32x4 w; w.x = pk2(a[0][0], a[0][1]); w.y = pk2(a[0][2], a[0][3]); w.z = pk2(a[1][0], a[1][1]); w.w = pk2(a[1][2], a[1][3]);
;                     *(u32x4*)(ACT + (size_t)row * FF + ch0) = w; }
;                 gprev[0] = g[0]; gprev[1] = g[1]; }
;         }
.LBB0_801:
	s_or_b64 exec, exec, s[18:19]
	v_mov_b32_e32 v17, v16
	v_mov_b32_e32 v18, v16
	v_mov_b32_e32 v19, v16
	v_pk_mul_f32 v[10:11], v[10:11], v[18:19]
	v_pk_mul_f32 v[8:9], v[8:9], v[16:17]
	v_mov_b32_dpp v59, v20 row_ror:1 row_mask:0xf bank_mask:0xf
	v_mov_b32_dpp v61, v20 row_ror:2 row_mask:0xf bank_mask:0xf
	v_mov_b32_dpp v62, v21 row_ror:1 row_mask:0xf bank_mask:0xf
	v_mov_b32_dpp v80, v21 row_ror:2 row_mask:0xf bank_mask:0xf
	v_mov_b32_dpp v81, v22 row_ror:1 row_mask:0xf bank_mask:0xf
	v_mov_b32_dpp v83, v22 row_ror:2 row_mask:0xf bank_mask:0xf
	v_mov_b32_dpp v58, v8 row_ror:1 row_mask:0xf bank_mask:0xf
	v_mov_b32_dpp v60, v8 row_ror:2 row_mask:0xf bank_mask:0xf
	v_mov_b32_dpp v20, v9 row_ror:1 row_mask:0xf bank_mask:0xf
	v_mov_b32_dpp v63, v9 row_ror:2 row_mask:0xf bank_mask:0xf
	v_mov_b32_dpp v21, v10 row_ror:1 row_mask:0xf bank_mask:0xf
	v_mov_b32_dpp v82, v10 row_ror:2 row_mask:0xf bank_mask:0xf
	v_mov_b32_dpp v22, v11 row_ror:1 row_mask:0xf bank_mask:0xf
	v_mov_b32_dpp v84, v23 row_ror:1 row_mask:0xf bank_mask:0xf
	v_mov_b32_dpp v85, v11 row_ror:2 row_mask:0xf bank_mask:0xf
	v_mov_b32_dpp v86, v23 row_ror:2 row_mask:0xf bank_mask:0xf
	s_and_saveexec_b64 s[18:19], s[62:63]
	s_cbranch_execz .LBB0_803
	global_store_dwordx4 v[24:25], v[8:11], off offset:16
.LBB0_803:
	s_or_b64 exec, exec, s[18:19]
	v_cndmask_b32_e64 v24, v83, v82, s[8:9]
	v_cndmask_b32_e64 v25, v86, v85, s[8:9]
	v_cndmask_b32_e64 v82, v21, v81, s[6:7]
	v_cndmask_b32_e64 v83, v22, v84, s[6:7]
	v_pk_fma_f32 v[22:23], v[74:75], v[24:25], v[78:79]
	v_cndmask_b32_e64 v58, v58, v59, s[6:7]
	v_pk_fma_f32 v[22:23], v[66:67], v[82:83], v[22:23]
	v_cndmask_b32_e64 v59, v20, v62, s[6:7]
	v_pk_fma_f32 v[10:11], v[70:71], v[10:11], v[22:23]
	v_pk_mul_f32 v[6:7], v[6:7], v[18:19]
	v_mul_f32_e32 v21, 0xbfb8aa3b, v10
	v_exp_f32_e32 v22, v21
	v_mul_f32_e32 v21, 0xbfb8aa3b, v11
	v_exp_f32_e32 v23, v21
	v_pk_mul_f32 v[4:5], v[4:5], v[16:17]
	v_pk_mul_f32 v[0:1], v[0:1], v[16:17]
	v_cndmask_b32_e64 v17, v34, v37, s[8:9]
	v_pk_add_f32 v[22:23], v[22:23], 1.0 op_sel_hi:[1,0]
	v_pk_mul_f32 v[2:3], v[2:3], v[18:19]
	v_rcp_f32_e32 v24, v23
	v_cndmask_b32_e64 v19, v36, v33, s[6:7]
	v_cndmask_b32_e64 v18, v32, v28, s[6:7]
	v_rcp_f32_e32 v70, v22
	v_mul_f32_e32 v11, v11, v24
	v_cndmask_b32_e64 v24, v61, v60, s[8:9]
	v_cndmask_b32_e64 v25, v80, v63, s[8:9]
	v_pk_fma_f32 v[20:21], v[72:73], v[24:25], v[76:77]
	v_pk_fma_f32 v[20:21], v[64:65], v[58:59], v[20:21]
	v_pk_fma_f32 v[8:9], v[68:69], v[8:9], v[20:21]
	v_mul_f32_e32 v20, 0xbfb8aa3b, v8
	v_mul_f32_e32 v21, 0xbfb8aa3b, v9
	v_exp_f32_e32 v20, v20
	v_exp_f32_e32 v21, v21
	s_nop 0
	v_pk_add_f32 v[20:21], v[20:21], 1.0 op_sel_hi:[1,0]
	v_mul_f32_e32 v10, v10, v70
	v_rcp_f32_e32 v25, v21
	v_pk_mul_f32 v[6:7], v[6:7], v[10:11]
	v_cndmask_b32_e64 v23, v56, v30, s[6:7]
	v_rcp_f32_e32 v24, v20
	v_mul_f32_e32 v9, v9, v25
	v_cndmask_b32_e64 v11, v31, v57, s[8:9]
	v_cndmask_b32_e64 v10, v27, v39, s[8:9]
	v_cndmask_b32_e64 v22, v38, v26, s[6:7]
	v_pk_fma_f32 v[10:11], v[46:47], v[10:11], v[54:55]
	v_pk_fma_f32 v[10:11], v[42:43], v[22:23], v[10:11]
	v_mul_f32_e32 v8, v8, v24
	v_pk_fma_f32 v[10:11], v[50:51], v[14:15], v[10:11]
	v_pk_mul_f32 v[4:5], v[4:5], v[8:9]
	v_mul_f32_e32 v14, 0xbfb8aa3b, v10
	v_mul_f32_e32 v15, 0xbfb8aa3b, v11
	v_exp_f32_e32 v14, v14
	v_exp_f32_e32 v15, v15
	s_nop 0
	v_pk_add_f32 v[14:15], v[14:15], 1.0 op_sel_hi:[1,0]
	s_nop 0
	v_rcp_f32_e32 v21, v15
	s_nop 0
	v_cndmask_b32_e64 v16, v29, v35, s[8:9]
	v_pk_fma_f32 v[16:17], v[44:45], v[16:17], v[52:53]
	v_pk_fma_f32 v[16:17], v[40:41], v[18:19], v[16:17]
	v_rcp_f32_e32 v22, v14
	v_pk_fma_f32 v[12:13], v[48:49], v[12:13], v[16:17]
	v_mul_f32_e32 v9, v11, v21
	v_mul_f32_e32 v15, 0xbfb8aa3b, v12
	v_exp_f32_e32 v16, v15
	v_mul_f32_e32 v15, 0xbfb8aa3b, v13
	v_exp_f32_e32 v17, v15
	s_nop 0
	v_pk_add_f32 v[16:17], v[16:17], 1.0 op_sel_hi:[1,0]
	v_rcp_f32_e32 v18, v17
	v_mul_f32_e32 v8, v10, v22
	v_pk_mul_f32 v[2:3], v[2:3], v[8:9]
	v_rcp_f32_e32 v11, v16
	v_mul_f32_e32 v9, v13, v18
	v_mul_f32_e32 v8, v12, v11
	v_pk_mul_f32 v[0:1], v[0:1], v[8:9]
	s_andn2_b64 vcc, exec, s[12:13]
	v_cvt_pk_bf16_f32 v0, v0, v1
	v_cvt_pk_bf16_f32 v1, v2, v3
	v_cvt_pk_bf16_f32 v2, v4, v5
	v_mov_b64_e32 v[4:5], s[44:45]
	v_mad_i64_i32 v[4:5], s[16:17], v182, s33, v[4:5]
	v_cvt_pk_bf16_f32 v3, v6, v7
	v_lshl_add_u64 v[4:5], v[180:181], 1, v[4:5]
	s_mov_b64 s[12:13], -1
	global_store_dwordx4 v[4:5], v[0:3], off
	s_cbranch_vccnz .LBB0_782
	s_and_b64 vcc, exec, s[14:15]
	s_cbranch_vccnz .LBB0_781
	s_barrier
	s_branch .LBB0_781
